# opt16b: row-scale block issued behind the fourteen prologue DMA pieces (7 of 8 phases), its barrier removed; on v064
# baseline (speedup 1.0000x reference)
.LBB0_203:
	v_lshrrev_b32_e32 v2, 1, v128
	v_and_b32_e32 v132, 24, v2
	v_lshrrev_b32_e32 v2, 5, v128
	v_and_b32_e32 v2, 4, v2
	v_bfe_u32 v3, v128, 2, 2
	v_lshlrev_b32_e32 v0, 4, v128
	v_and_b32_e32 v1, 32, v128
	v_bfe_u32 v11, v128, 2, 4
	v_or3_b32 v2, v2, v3, v132
	v_lshrrev_b32_e32 v3, 3, v128
	s_movk_i32 s1, 0x70
	v_bitop3_b32 v9, v0, v1, 48 bitop3:0x6c
	v_and_b32_e32 v10, 64, v128
	v_and_or_b32 v4, v3, s1, v11
	s_movk_i32 s1, 0x60
	v_add_u32_e32 v12, 0x2000, v0
	s_lshr_b32 s5, s8, 6
	s_lshr_b32 s4, s8, 8
	v_or_b32_e32 v1, v9, v10
	v_and_or_b32 v3, v3, s1, v2
	v_lshrrev_b32_e32 v0, 7, v12
	s_movk_i32 s1, 0xf0
	s_lshl_b32 s58, s5, 10
	v_lshl_or_b32 v136, v3, 11, v1
	v_and_or_b32 v3, v0, s1, v11
	s_movk_i32 s1, 0xe0
	s_add_u32 s59, s70, 0x100000
	v_and_or_b32 v0, v0, s1, v2
	s_addc_u32 s62, s71, 0
	s_ashr_i32 s7, s6, 31
	s_ashr_i32 s1, s0, 31
	s_lshl_b64 s[10:11], s[6:7], 19
	s_lshl_b64 s[12:13], s[0:1], 19
	s_add_u32 s52, s59, s12
	s_addc_u32 s53, s62, s13
	s_add_i32 s63, s58, 0
	s_add_i32 m0, s63, 0x10000
	v_lshl_or_b32 v140, v0, 11, v1
	global_load_lds_dwordx4 v136, s[52:53]
	s_add_i32 m0, s63, 0x12000
	s_add_u32 s12, s52, 0x40000
	global_load_lds_dwordx4 v140, s[52:53]
	s_addc_u32 s13, s53, 0
	s_add_i32 m0, s63, 0x14000
	v_lshl_or_b32 v134, v4, 11, v1
	global_load_lds_dwordx4 v136, s[12:13]
	s_add_i32 m0, s63, 0x16000
	s_add_u32 s50, s14, s10
	s_addc_u32 s51, s15, s11
	s_add_i32 s64, s63, 0x2000
	global_load_lds_dwordx4 v140, s[12:13]
	s_mov_b32 m0, s63
	s_add_u32 s10, s50, 0x40000
	v_lshl_or_b32 v138, v3, 11, v1
	global_load_lds_dwordx4 v134, s[50:51]
	s_mov_b32 m0, s64
	s_addc_u32 s11, s51, 0
	s_add_i32 s65, s63, 0x4000
	global_load_lds_dwordx4 v138, s[50:51]
	s_mov_b32 m0, s65
	s_add_i32 s66, s63, 0x6000
	global_load_lds_dwordx4 v134, s[10:11]
	s_mov_b32 m0, s66
	v_mov_b32_e32 v143, 0
	global_load_lds_dwordx4 v138, s[10:11]
	v_mov_b32_e32 v137, v143
	v_mov_b32_e32 v141, v143
	v_mov_b32_e32 v135, v143
	v_mov_b32_e32 v139, v143
	s_cmp_eq_u32 s4, 1
	s_mov_b32 s9, 0
	v_lshl_add_u64 v[6:7], s[52:53], 0, v[136:137]
	v_lshl_add_u64 v[4:5], s[52:53], 0, v[140:141]
	v_lshl_add_u64 v[0:1], s[50:51], 0, v[134:135]
	s_cselect_b64 s[10:11], -1, 0
	v_lshl_add_u64 v[2:3], s[50:51], 0, v[138:139]
	s_add_u32 s20, s70, 0x13700000
	s_addc_u32 s21, s71, 0
	s_lshl_b32 s5, s5, 5
	s_mov_b64 s[22:23], 0x80
	s_and_b32 s67, s5, 0x60
	s_add_i32 m0, s63, 0x18000
	v_lshl_add_u64 v[6:7], v[6:7], 0, s[22:23]
	s_lshl_b32 s1, s4, 13
	s_lshl_b32 s5, s67, 7
	global_load_lds_dwordx4 v[6:7], off
	v_lshl_add_u64 v[4:5], v[4:5], 0, s[22:23]
	s_add_i32 m0, s63, 0x1a000
	s_add_i32 s79, s63, 0x8000
	s_add_i32 s81, s63, 0xa000
	global_load_lds_dwordx4 v[4:5], off
	v_lshl_add_u64 v[0:1], v[0:1], 0, s[22:23]
	s_mov_b32 m0, s79
	s_add_u32 s12, s52, 0x40080
	global_load_lds_dwordx4 v[0:1], off
	v_lshl_add_u64 v[0:1], v[2:3], 0, s[22:23]
	s_mov_b32 m0, s81
	s_addc_u32 s13, s53, 0
	global_load_lds_dwordx4 v[0:1], off
	s_add_i32 m0, s63, 0x1c000
	v_lshl_add_u64 v[0:1], s[12:13], 0, v[136:137]
	global_load_lds_dwordx4 v[0:1], off
	v_lshl_add_u64 v[0:1], s[12:13], 0, v[140:141]
	s_add_i32 m0, s63, 0x1e000
	global_load_lds_dwordx4 v[0:1], off
	v_and_b32_e32 v114, 0xff, v128
	s_lshr_b32 s98, s91, 2
	v_mov_b32_e32 v115, 0x358637bd
	s_mul_i32 s99, s98, s72
	s_add_i32 s99, s99, s2
	s_cmp_lt_u32 s99, 0x600
	s_cselect_b32 s99, s99, s2
	s_and_b32 s100, s99, 7
	s_mul_i32 s100, s100, 0xc0
	s_lshr_b32 s101, s99, 3
	s_add_i32 s100, s100, s101
	s_mul_hi_u32 s101, s100, 0x2aaaaab
	s_lshl_b32 s101, s101, 3
	s_and_b32 s100, s100, 7
	s_or_b32 s101, s101, s100
	s_lshl_b32 s101, s101, 8
	v_add_u32_e32 v112, s101, v114
	v_lshlrev_b32_e32 v112, 6, v112
	v_mov_b32_e32 v113, 0
	v_lshl_add_u64 v[112:113], s[18:19], 0, v[112:113]
	global_load_dwordx4 v[16:19], v[112:113], off
	global_load_dwordx4 v[20:23], v[112:113], off offset:16
	global_load_dwordx4 v[24:27], v[112:113], off offset:32
	global_load_dwordx4 v[28:31], v[112:113], off offset:48
	s_add_i32 s98, s98, 2
	s_mul_i32 s99, s98, s72
	s_add_i32 s99, s99, s2
	s_cmp_lt_u32 s99, 0x600
	s_cselect_b32 s99, s99, s2
	s_and_b32 s100, s99, 7
	s_mul_i32 s100, s100, 0xc0
	s_lshr_b32 s101, s99, 3
	s_add_i32 s100, s100, s101
	s_mul_hi_u32 s101, s100, 0x2aaaaab
	s_lshl_b32 s101, s101, 3
	s_and_b32 s100, s100, 7
	s_or_b32 s101, s101, s100
	s_lshl_b32 s101, s101, 8
	v_add_u32_e32 v112, s101, v114
	v_lshlrev_b32_e32 v112, 6, v112
	v_mov_b32_e32 v113, 0
	v_lshl_add_u64 v[112:113], s[18:19], 0, v[112:113]
	global_load_dwordx4 v[32:35], v[112:113], off
	global_load_dwordx4 v[36:39], v[112:113], off offset:16
	global_load_dwordx4 v[40:43], v[112:113], off offset:32
	global_load_dwordx4 v[44:47], v[112:113], off offset:48
	s_add_i32 s98, s98, 2
	s_mul_i32 s99, s98, s72
	s_add_i32 s99, s99, s2
	s_cmp_lt_u32 s99, 0x600
	s_cselect_b32 s99, s99, s2
	s_and_b32 s100, s99, 7
	s_mul_i32 s100, s100, 0xc0
	s_lshr_b32 s101, s99, 3
	s_add_i32 s100, s100, s101
	s_mul_hi_u32 s101, s100, 0x2aaaaab
	s_lshl_b32 s101, s101, 3
	s_and_b32 s100, s100, 7
	s_or_b32 s101, s101, s100
	s_lshl_b32 s101, s101, 8
	v_add_u32_e32 v112, s101, v114
	v_lshlrev_b32_e32 v112, 6, v112
	v_mov_b32_e32 v113, 0
	v_lshl_add_u64 v[112:113], s[18:19], 0, v[112:113]
	global_load_dwordx4 v[48:51], v[112:113], off
	global_load_dwordx4 v[52:55], v[112:113], off offset:16
	global_load_dwordx4 v[56:59], v[112:113], off offset:32
	global_load_dwordx4 v[60:63], v[112:113], off offset:48
	s_add_i32 s98, s98, 2
	v_lshlrev_b32_e32 v116, 2, v128
	v_add_u32_e32 v116, 0x20000, v116
	s_waitcnt vmcnt(8)
	v_pk_add_f32 v[118:119], v[18:19], v[22:23]
	v_pk_add_f32 v[120:121], v[16:17], v[20:21]
	v_pk_add_f32 v[122:123], v[26:27], v[30:31]
	v_pk_add_f32 v[124:125], v[24:25], v[28:29]
	v_pk_add_f32 v[118:119], v[118:119], v[122:123]
	v_pk_add_f32 v[120:121], v[120:121], v[124:125]
	v_add_f32_e32 v120, v121, v120
	v_add_f32_e32 v118, v118, v119
	v_add_f32_e32 v118, v120, v118
	v_fmamk_f32 v118, v118, 0x3a800000, v115
	v_rsq_f32_e32 v118, v118
	ds_write_b32 v116, v118
	s_waitcnt vmcnt(4)
	v_pk_add_f32 v[118:119], v[34:35], v[38:39]
	v_pk_add_f32 v[120:121], v[32:33], v[36:37]
	v_pk_add_f32 v[122:123], v[42:43], v[46:47]
	v_pk_add_f32 v[124:125], v[40:41], v[44:45]
	v_pk_add_f32 v[118:119], v[118:119], v[122:123]
	v_pk_add_f32 v[120:121], v[120:121], v[124:125]
	v_add_f32_e32 v120, v121, v120
	v_add_f32_e32 v118, v118, v119
	v_add_f32_e32 v118, v120, v118
	v_fmamk_f32 v118, v118, 0x3a800000, v115
	v_rsq_f32_e32 v118, v118
	ds_write_b32 v116, v118 offset:2048
	s_waitcnt vmcnt(0)
	v_pk_add_f32 v[118:119], v[50:51], v[54:55]
	v_pk_add_f32 v[120:121], v[48:49], v[52:53]
	v_pk_add_f32 v[122:123], v[58:59], v[62:63]
	v_pk_add_f32 v[124:125], v[56:57], v[60:61]
	v_pk_add_f32 v[118:119], v[118:119], v[122:123]
	v_pk_add_f32 v[120:121], v[120:121], v[124:125]
	v_add_f32_e32 v120, v121, v120
	v_add_f32_e32 v118, v118, v119
	v_add_f32_e32 v118, v120, v118
	v_fmamk_f32 v118, v118, 0x3a800000, v115
	v_rsq_f32_e32 v118, v118
	ds_write_b32 v116, v118 offset:4096
	s_cmp_lg_u32 s4, 1
	s_cbranch_scc1 .LBB0_205
	s_barrier
.LBB0_205:
	s_waitcnt vmcnt(8) lgkmcnt(0)
	s_barrier
	s_cmpk_lt_u32 s8, 0x100
	v_and_b32_e32 v0, 15, v128
	v_lshlrev_b32_e32 v1, 1, v132
	v_lshl_or_b32 v131, s4, 6, v0
	v_lshl_or_b32 v2, v0, 6, v1
	v_lshlrev_b32_e32 v0, 2, v0
	v_and_b32_e32 v3, 32, v0
	v_bitop3_b32 v2, v2, s1, v3 bitop3:0xde
	v_lshlrev_b32_e32 v3, 6, v128
	s_movk_i32 s1, 0x3c0
	v_and_or_b32 v1, v3, s1, v1
	s_cselect_b64 s[26:27], -1, 0
	s_lshl_b32 s1, s4, 8
	s_add_i32 s1, s1, 0
	s_add_i32 s1, s1, 0x20000
	v_and_b32_e32 v3, 32, v8
	v_add_u32_e32 v156, s1, v0
	v_lshlrev_b32_e32 v0, 8, v128
	v_bitop3_b32 v133, s5, v1, v3 bitop3:0xf6
	v_and_b32_e32 v0, 0x38000, v0
	v_lshlrev_b32_e32 v1, 11, v11
	v_or3_b32 v0, v9, v0, v1
	v_add_u32_e32 v144, v0, v10
	v_lshlrev_b32_e32 v0, 4, v12
	s_waitcnt vmcnt(6)
	v_and_b32_e32 v0, 0x78000, v0
	v_or3_b32 v0, v9, v0, v1
	s_add_i32 s82, 0, 0x10000
	s_add_i32 s83, 0, 0x14000
	v_mov_b32_e32 v145, v143
	v_add_u32_e32 v146, v0, v10
	v_mov_b32_e32 v147, v143
	v_mov_b64_e32 v[148:149], 0x600
	v_mov_b64_e32 v[150:151], 0x5ff
	s_movk_i32 s77, 0xc1
	v_add_u32_e32 v157, s82, v133
	v_add_u32_e32 v158, s83, v133
	v_add_u32_e32 v159, 0, v2
	s_mov_b32 s1, 0
	s_mov_b32 s84, 0
	s_barrier
	s_branch .LBB0_208

.LBB0_467:
	s_or_b64 exec, exec, s[0:1]
	s_cmpk_gt_i32 s2, 0xaff
	v_readfirstlane_b32 s5, v128
	s_cbranch_scc1 .LBB0_483
	v_lshrrev_b32_e32 v0, 5, v128
	v_lshrrev_b32_e32 v2, 1, v128
	v_and_b32_e32 v0, 4, v0
	v_bfe_u32 v1, v128, 2, 2
	v_and_b32_e32 v12, 24, v2
	v_or3_b32 v0, v0, v1, v12
	v_lshlrev_b32_e32 v1, 4, v128
	v_add_u32_e32 v9, 0x2000, v1
	v_lshrrev_b32_e32 v2, 7, v9
	s_movk_i32 s0, 0xe0
	v_and_b32_e32 v4, 32, v128
	v_and_or_b32 v3, v2, s0, v0
	v_bitop3_b32 v10, v1, v4, 48 bitop3:0x6c
	v_and_b32_e32 v11, 64, v128
	v_bfe_u32 v13, v128, 2, 4
	s_movk_i32 s0, 0xf0
	s_lshr_b32 s6, s5, 6
	v_or_b32_e32 v1, v10, v11
	v_and_or_b32 v2, v2, s0, v13
	s_lshr_b32 s10, s5, 8
	s_lshl_b32 s54, s6, 10
	v_lshl_or_b32 v134, v2, 11, v1
	v_lshrrev_b32_e32 v2, 3, v128
	s_movk_i32 s0, 0x60
	s_add_u32 s55, s70, 0x900000
	v_and_or_b32 v0, v2, s0, v0
	s_movk_i32 s0, 0x70
	s_addc_u32 s56, s71, 0
	v_lshl_or_b32 v136, v0, 11, v1
	v_and_or_b32 v0, v2, s0, v13
	s_lshr_b32 s0, s3, 29
	s_add_i32 s0, s2, s0
	s_ashr_i32 s1, s0, 3
	s_and_b32 s0, s0, -8
	s_sub_i32 s0, s2, s0
	s_cmp_lt_i32 s0, 0
	s_movk_i32 s57, 0x161
	s_cselect_b32 s4, s57, 0x160
	s_mul_i32 s0, s0, s4
	s_add_i32 s0, s0, s1
	s_mul_hi_i32 s1, s0, 0x2e8ba2e9
	s_lshr_b32 s4, s1, 31
	s_ashr_i32 s1, s1, 5
	s_add_i32 s1, s1, s4
	s_lshl_b32 s7, s1, 3
	s_mulk_i32 s1, 0xb0
	s_sub_i32 s0, s0, s1
	s_bfe_u32 s1, s0, 0x3001c
	s_add_i32 s1, s0, s1
	s_sext_i32_i16 s4, s1
	s_and_b32 s1, s1, 0xfff8
	s_sub_i32 s0, s0, s1
	s_sext_i32_i16 s0, s0
	s_lshr_b32 s4, s4, 3
	s_add_i32 s40, s7, s0
	s_ashr_i32 s41, s40, 31
	s_bfe_i64 s[8:9], s[4:5], 0x100000
	s_lshl_b64 s[0:1], s[40:41], 19
	s_lshl_b64 s[8:9], s[8:9], 19
	s_add_u32 s48, s55, s8
	s_addc_u32 s49, s56, s9
	s_add_i32 s41, s54, 0
	s_add_i32 m0, s41, 0x10000
	v_lshl_or_b32 v132, v3, 11, v1
	global_load_lds_dwordx4 v136, s[48:49]
	s_add_i32 m0, s41, 0x12000
	s_add_u32 s8, s48, 0x40000
	global_load_lds_dwordx4 v132, s[48:49]
	s_addc_u32 s9, s49, 0
	s_add_i32 m0, s41, 0x14000
	v_lshl_or_b32 v138, v0, 11, v1
	global_load_lds_dwordx4 v136, s[8:9]
	s_add_i32 m0, s41, 0x16000
	s_add_u32 s42, s14, s0
	s_addc_u32 s43, s15, s1
	s_add_i32 s58, s41, 0x2000
	global_load_lds_dwordx4 v132, s[8:9]
	s_mov_b32 m0, s41
	s_add_u32 s0, s42, 0x40000
	global_load_lds_dwordx4 v138, s[42:43]
	s_mov_b32 m0, s58
	s_addc_u32 s1, s43, 0
	s_add_i32 s59, s41, 0x4000
	global_load_lds_dwordx4 v134, s[42:43]
	s_mov_b32 m0, s59
	s_add_i32 s62, s41, 0x6000
	global_load_lds_dwordx4 v138, s[0:1]
	s_mov_b32 m0, s62
	v_mov_b32_e32 v137, 0
	global_load_lds_dwordx4 v134, s[0:1]
	v_mov_b32_e32 v133, v137
	v_mov_b32_e32 v139, v137
	v_mov_b32_e32 v135, v137
	s_cmp_eq_u32 s10, 1
	s_mov_b32 s12, 0
	v_lshl_add_u64 v[6:7], s[48:49], 0, v[136:137]
	v_lshl_add_u64 v[4:5], s[48:49], 0, v[132:133]
	v_lshl_add_u64 v[0:1], s[42:43], 0, v[138:139]
	s_cselect_b64 s[0:1], -1, 0
	v_lshl_add_u64 v[2:3], s[42:43], 0, v[134:135]
	s_lshl_b32 s6, s6, 5
	s_and_b32 s22, s6, 0x60
	s_mov_b64 s[6:7], 0x80
	s_add_i32 m0, s41, 0x18000
	v_lshl_add_u64 v[6:7], v[6:7], 0, s[6:7]
	s_lshl_b32 s11, s10, 13
	s_lshl_b32 s23, s22, 7
	global_load_lds_dwordx4 v[6:7], off
	v_lshl_add_u64 v[4:5], v[4:5], 0, s[6:7]
	s_add_i32 m0, s41, 0x1a000
	s_add_i32 s63, s41, 0x8000
	s_add_i32 s64, s41, 0xa000
	global_load_lds_dwordx4 v[4:5], off
	v_lshl_add_u64 v[0:1], v[0:1], 0, s[6:7]
	s_mov_b32 m0, s63
	s_add_u32 s8, s48, 0x40080
	global_load_lds_dwordx4 v[0:1], off
	v_lshl_add_u64 v[0:1], v[2:3], 0, s[6:7]
	s_mov_b32 m0, s64
	s_addc_u32 s9, s49, 0
	global_load_lds_dwordx4 v[0:1], off
	s_add_i32 m0, s41, 0x1c000
	v_lshl_add_u64 v[0:1], s[8:9], 0, v[136:137]
	global_load_lds_dwordx4 v[0:1], off
	v_lshl_add_u64 v[0:1], s[8:9], 0, v[132:133]
	s_add_i32 m0, s41, 0x1e000
	s_sext_i32_i16 s13, s4
	global_load_lds_dwordx4 v[0:1], off
	v_and_b32_e32 v114, 0xff, v128
	s_lshr_b32 s98, s91, 2
	v_mov_b32_e32 v115, 0x358637bd
	s_mul_i32 s99, s98, s72
	s_add_i32 s99, s99, s2
	s_cmp_lt_u32 s99, 0xb00
	s_cselect_b32 s99, s99, s2
	s_and_b32 s100, s99, 7
	s_mul_i32 s100, s100, 0x160
	s_lshr_b32 s101, s99, 3
	s_add_i32 s100, s100, s101
	s_mul_hi_u32 s101, s100, 0x1745d18
	s_lshl_b32 s101, s101, 3
	s_and_b32 s100, s100, 7
	s_or_b32 s101, s101, s100
	s_lshl_b32 s101, s101, 8
	v_add_u32_e32 v112, s101, v114
	v_lshlrev_b32_e32 v112, 6, v112
	v_mov_b32_e32 v113, 0
	v_lshl_add_u64 v[112:113], s[18:19], 0, v[112:113]
	global_load_dwordx4 v[16:19], v[112:113], off
	global_load_dwordx4 v[20:23], v[112:113], off offset:16
	global_load_dwordx4 v[24:27], v[112:113], off offset:32
	global_load_dwordx4 v[28:31], v[112:113], off offset:48
	s_add_i32 s98, s98, 2
	s_mul_i32 s99, s98, s72
	s_add_i32 s99, s99, s2
	s_cmp_lt_u32 s99, 0xb00
	s_cselect_b32 s99, s99, s2
	s_and_b32 s100, s99, 7
	s_mul_i32 s100, s100, 0x160
	s_lshr_b32 s101, s99, 3
	s_add_i32 s100, s100, s101
	s_mul_hi_u32 s101, s100, 0x1745d18
	s_lshl_b32 s101, s101, 3
	s_and_b32 s100, s100, 7
	s_or_b32 s101, s101, s100
	s_lshl_b32 s101, s101, 8
	v_add_u32_e32 v112, s101, v114
	v_lshlrev_b32_e32 v112, 6, v112
	v_mov_b32_e32 v113, 0
	v_lshl_add_u64 v[112:113], s[18:19], 0, v[112:113]
	global_load_dwordx4 v[32:35], v[112:113], off
	global_load_dwordx4 v[36:39], v[112:113], off offset:16
	global_load_dwordx4 v[40:43], v[112:113], off offset:32
	global_load_dwordx4 v[44:47], v[112:113], off offset:48
	s_add_i32 s98, s98, 2
	s_mul_i32 s99, s98, s72
	s_add_i32 s99, s99, s2
	s_cmp_lt_u32 s99, 0xb00
	s_cselect_b32 s99, s99, s2
	s_and_b32 s100, s99, 7
	s_mul_i32 s100, s100, 0x160
	s_lshr_b32 s101, s99, 3
	s_add_i32 s100, s100, s101
	s_mul_hi_u32 s101, s100, 0x1745d18
	s_lshl_b32 s101, s101, 3
	s_and_b32 s100, s100, 7
	s_or_b32 s101, s101, s100
	s_lshl_b32 s101, s101, 8
	v_add_u32_e32 v112, s101, v114
	v_lshlrev_b32_e32 v112, 6, v112
	v_mov_b32_e32 v113, 0
	v_lshl_add_u64 v[112:113], s[18:19], 0, v[112:113]
	global_load_dwordx4 v[48:51], v[112:113], off
	global_load_dwordx4 v[52:55], v[112:113], off offset:16
	global_load_dwordx4 v[56:59], v[112:113], off offset:32
	global_load_dwordx4 v[60:63], v[112:113], off offset:48
	s_add_i32 s98, s98, 2
	s_mul_i32 s99, s98, s72
	s_add_i32 s99, s99, s2
	s_cmp_lt_u32 s99, 0xb00
	s_cselect_b32 s99, s99, s2
	s_and_b32 s100, s99, 7
	s_mul_i32 s100, s100, 0x160
	s_lshr_b32 s101, s99, 3
	s_add_i32 s100, s100, s101
	s_mul_hi_u32 s101, s100, 0x1745d18
	s_lshl_b32 s101, s101, 3
	s_and_b32 s100, s100, 7
	s_or_b32 s101, s101, s100
	s_lshl_b32 s101, s101, 8
	v_add_u32_e32 v112, s101, v114
	v_lshlrev_b32_e32 v112, 6, v112
	v_mov_b32_e32 v113, 0
	v_lshl_add_u64 v[112:113], s[18:19], 0, v[112:113]
	global_load_dwordx4 v[64:67], v[112:113], off
	global_load_dwordx4 v[68:71], v[112:113], off offset:16
	global_load_dwordx4 v[72:75], v[112:113], off offset:32
	global_load_dwordx4 v[76:79], v[112:113], off offset:48
	s_add_i32 s98, s98, 2
	s_mul_i32 s99, s98, s72
	s_add_i32 s99, s99, s2
	s_cmp_lt_u32 s99, 0xb00
	s_cselect_b32 s99, s99, s2
	s_and_b32 s100, s99, 7
	s_mul_i32 s100, s100, 0x160
	s_lshr_b32 s101, s99, 3
	s_add_i32 s100, s100, s101
	s_mul_hi_u32 s101, s100, 0x1745d18
	s_lshl_b32 s101, s101, 3
	s_and_b32 s100, s100, 7
	s_or_b32 s101, s101, s100
	s_lshl_b32 s101, s101, 8
	v_add_u32_e32 v112, s101, v114
	v_lshlrev_b32_e32 v112, 6, v112
	v_mov_b32_e32 v113, 0
	v_lshl_add_u64 v[112:113], s[18:19], 0, v[112:113]
	global_load_dwordx4 v[80:83], v[112:113], off
	global_load_dwordx4 v[84:87], v[112:113], off offset:16
	global_load_dwordx4 v[88:91], v[112:113], off offset:32
	global_load_dwordx4 v[92:95], v[112:113], off offset:48
	s_add_i32 s98, s98, 2
	s_mul_i32 s99, s98, s72
	s_add_i32 s99, s99, s2
	s_cmp_lt_u32 s99, 0xb00
	s_cselect_b32 s99, s99, s2
	s_and_b32 s100, s99, 7
	s_mul_i32 s100, s100, 0x160
	s_lshr_b32 s101, s99, 3
	s_add_i32 s100, s100, s101
	s_mul_hi_u32 s101, s100, 0x1745d18
	s_lshl_b32 s101, s101, 3
	s_and_b32 s100, s100, 7
	s_or_b32 s101, s101, s100
	s_lshl_b32 s101, s101, 8
	v_add_u32_e32 v112, s101, v114
	v_lshlrev_b32_e32 v112, 6, v112
	v_mov_b32_e32 v113, 0
	v_lshl_add_u64 v[112:113], s[18:19], 0, v[112:113]
	global_load_dwordx4 v[96:99], v[112:113], off
	global_load_dwordx4 v[100:103], v[112:113], off offset:16
	global_load_dwordx4 v[104:107], v[112:113], off offset:32
	global_load_dwordx4 v[108:111], v[112:113], off offset:48
	s_add_i32 s98, s98, 2
	v_lshlrev_b32_e32 v116, 2, v128
	v_add_u32_e32 v116, 0x20000, v116
	s_waitcnt vmcnt(20)
	v_pk_add_f32 v[118:119], v[18:19], v[22:23]
	v_pk_add_f32 v[120:121], v[16:17], v[20:21]
	v_pk_add_f32 v[122:123], v[26:27], v[30:31]
	v_pk_add_f32 v[124:125], v[24:25], v[28:29]
	v_pk_add_f32 v[118:119], v[118:119], v[122:123]
	v_pk_add_f32 v[120:121], v[120:121], v[124:125]
	v_add_f32_e32 v120, v121, v120
	v_add_f32_e32 v118, v118, v119
	v_add_f32_e32 v118, v120, v118
	v_fmamk_f32 v118, v118, 0x3a800000, v115
	v_rsq_f32_e32 v118, v118
	ds_write_b32 v116, v118
	s_waitcnt vmcnt(16)
	v_pk_add_f32 v[118:119], v[34:35], v[38:39]
	v_pk_add_f32 v[120:121], v[32:33], v[36:37]
	v_pk_add_f32 v[122:123], v[42:43], v[46:47]
	v_pk_add_f32 v[124:125], v[40:41], v[44:45]
	v_pk_add_f32 v[118:119], v[118:119], v[122:123]
	v_pk_add_f32 v[120:121], v[120:121], v[124:125]
	v_add_f32_e32 v120, v121, v120
	v_add_f32_e32 v118, v118, v119
	v_add_f32_e32 v118, v120, v118
	v_fmamk_f32 v118, v118, 0x3a800000, v115
	v_rsq_f32_e32 v118, v118
	ds_write_b32 v116, v118 offset:2048
	s_waitcnt vmcnt(12)
	v_pk_add_f32 v[118:119], v[50:51], v[54:55]
	v_pk_add_f32 v[120:121], v[48:49], v[52:53]
	v_pk_add_f32 v[122:123], v[58:59], v[62:63]
	v_pk_add_f32 v[124:125], v[56:57], v[60:61]
	v_pk_add_f32 v[118:119], v[118:119], v[122:123]
	v_pk_add_f32 v[120:121], v[120:121], v[124:125]
	v_add_f32_e32 v120, v121, v120
	v_add_f32_e32 v118, v118, v119
	v_add_f32_e32 v118, v120, v118
	v_fmamk_f32 v118, v118, 0x3a800000, v115
	v_rsq_f32_e32 v118, v118
	ds_write_b32 v116, v118 offset:4096
	s_waitcnt vmcnt(8)
	v_pk_add_f32 v[118:119], v[66:67], v[70:71]
	v_pk_add_f32 v[120:121], v[64:65], v[68:69]
	v_pk_add_f32 v[122:123], v[74:75], v[78:79]
	v_pk_add_f32 v[124:125], v[72:73], v[76:77]
	v_pk_add_f32 v[118:119], v[118:119], v[122:123]
	v_pk_add_f32 v[120:121], v[120:121], v[124:125]
	v_add_f32_e32 v120, v121, v120
	v_add_f32_e32 v118, v118, v119
	v_add_f32_e32 v118, v120, v118
	v_fmamk_f32 v118, v118, 0x3a800000, v115
	v_rsq_f32_e32 v118, v118
	ds_write_b32 v116, v118 offset:6144
	s_waitcnt vmcnt(4)
	v_pk_add_f32 v[118:119], v[82:83], v[86:87]
	v_pk_add_f32 v[120:121], v[80:81], v[84:85]
	v_pk_add_f32 v[122:123], v[90:91], v[94:95]
	v_pk_add_f32 v[124:125], v[88:89], v[92:93]
	v_pk_add_f32 v[118:119], v[118:119], v[122:123]
	v_pk_add_f32 v[120:121], v[120:121], v[124:125]
	v_add_f32_e32 v120, v121, v120
	v_add_f32_e32 v118, v118, v119
	v_add_f32_e32 v118, v120, v118
	v_fmamk_f32 v118, v118, 0x3a800000, v115
	v_rsq_f32_e32 v118, v118
	ds_write_b32 v116, v118 offset:8192
	s_waitcnt vmcnt(0)
	v_pk_add_f32 v[118:119], v[98:99], v[102:103]
	v_pk_add_f32 v[120:121], v[96:97], v[100:101]
	v_pk_add_f32 v[122:123], v[106:107], v[110:111]
	v_pk_add_f32 v[124:125], v[104:105], v[108:109]
	v_pk_add_f32 v[118:119], v[118:119], v[122:123]
	v_pk_add_f32 v[120:121], v[120:121], v[124:125]
	v_add_f32_e32 v120, v121, v120
	v_add_f32_e32 v118, v118, v119
	v_add_f32_e32 v118, v120, v118
	v_fmamk_f32 v118, v118, 0x3a800000, v115
	v_rsq_f32_e32 v118, v118
	ds_write_b32 v116, v118 offset:10240
	s_cmp_lg_u32 s10, 1
	s_cbranch_scc1 .LBB0_470
	s_barrier
.LBB0_470:
	s_waitcnt vmcnt(8) lgkmcnt(0)
	s_barrier
	v_and_b32_e32 v0, 15, v128
	v_lshlrev_b32_e32 v1, 1, v12
	v_lshl_or_b32 v131, s10, 6, v0
	v_lshl_or_b32 v2, v0, 6, v1
	v_lshlrev_b32_e32 v0, 2, v0
	v_and_b32_e32 v3, 32, v0
	v_bitop3_b32 v2, v2, s11, v3 bitop3:0xde
	v_lshlrev_b32_e32 v3, 6, v128
	s_movk_i32 s4, 0x3c0
	s_cmpk_lt_u32 s5, 0x100
	v_and_or_b32 v1, v3, s4, v1
	s_cselect_b64 s[8:9], -1, 0
	s_lshl_b32 s4, s10, 8
	s_add_i32 s4, s4, 0
	s_add_i32 s4, s4, 0x20000
	v_and_b32_e32 v3, 32, v8
	v_add_u32_e32 v153, s4, v0
	v_lshlrev_b32_e32 v0, 8, v128
	v_bitop3_b32 v152, s23, v1, v3 bitop3:0xf6
	v_and_b32_e32 v0, 0x38000, v0
	v_lshlrev_b32_e32 v1, 11, v13
	v_or3_b32 v0, v10, v0, v1
	v_add_u32_e32 v140, v0, v11
	v_lshlrev_b32_e32 v0, 4, v9
	s_waitcnt vmcnt(6)
	v_and_b32_e32 v0, 0x78000, v0
	v_or3_b32 v0, v10, v0, v1
	s_add_i32 s65, 0, 0x10000
	s_add_i32 s66, 0, 0x14000
	v_or_b32_e32 v154, s22, v12
	v_mov_b32_e32 v141, v137
	v_add_u32_e32 v142, v0, v11
	v_mov_b32_e32 v143, v137
	v_mov_b64_e32 v[144:145], 0xb00
	v_mov_b64_e32 v[146:147], 0xaff
	v_add_u32_e32 v155, s65, v152
	v_add_u32_e32 v157, s66, v152
	v_add_u32_e32 v158, 0, v2
	s_movk_i32 s67, 0x1600
	s_mov_b32 s77, 0
	s_barrier
	s_branch .LBB0_473

.LBB0_647:
	v_lshrrev_b32_e32 v2, 1, v128
	v_lshrrev_b32_e32 v3, 5, v128
	v_and_b32_e32 v2, 24, v2
	v_and_b32_e32 v3, 4, v3
	v_bfe_u32 v4, v128, 2, 2
	v_lshlrev_b32_e32 v0, 4, v128
	v_and_b32_e32 v1, 32, v128
	v_bfe_u32 v11, v128, 2, 4
	v_or3_b32 v2, v3, v4, v2
	v_lshrrev_b32_e32 v3, 3, v128
	s_movk_i32 s1, 0x70
	s_lshr_b32 s4, s6, 6
	v_bitop3_b32 v9, v0, v1, 48 bitop3:0x6c
	v_and_b32_e32 v10, 64, v128
	v_and_or_b32 v4, v3, s1, v11
	s_movk_i32 s1, 0x60
	v_add_u32_e32 v12, 0x2000, v0
	v_or_b32_e32 v1, v9, v10
	v_and_or_b32 v3, v3, s1, v2
	v_lshrrev_b32_e32 v0, 7, v12
	s_movk_i32 s1, 0xf0
	s_lshr_b32 s7, s6, 8
	s_lshl_b32 s62, s4, 10
	v_lshl_or_b32 v134, v3, 11, v1
	v_and_or_b32 v3, v0, s1, v11
	s_movk_i32 s1, 0xe0
	s_add_u32 s63, s70, 0x1980000
	v_and_or_b32 v0, v0, s1, v2
	s_addc_u32 s64, s71, 0
	s_ashr_i32 s9, s8, 31
	s_ashr_i32 s1, s0, 31
	s_lshl_b64 s[10:11], s[8:9], 19
	s_lshl_b64 s[12:13], s[0:1], 19
	s_add_u32 s54, s63, s12
	s_addc_u32 s55, s64, s13
	s_add_i32 s65, s62, 0
	s_add_i32 m0, s65, 0x10000
	v_lshl_or_b32 v138, v0, 11, v1
	global_load_lds_dwordx4 v134, s[54:55]
	s_add_i32 m0, s65, 0x12000
	s_add_u32 s12, s54, 0x40000
	global_load_lds_dwordx4 v138, s[54:55]
	s_addc_u32 s13, s55, 0
	s_add_i32 m0, s65, 0x14000
	v_lshl_or_b32 v132, v4, 11, v1
	global_load_lds_dwordx4 v134, s[12:13]
	s_add_i32 m0, s65, 0x16000
	s_add_u32 s52, s14, s10
	s_addc_u32 s53, s15, s11
	s_add_i32 s66, s65, 0x2000
	global_load_lds_dwordx4 v138, s[12:13]
	s_mov_b32 m0, s65
	s_add_u32 s10, s52, 0x40000
	v_lshl_or_b32 v136, v3, 11, v1
	global_load_lds_dwordx4 v132, s[52:53]
	s_mov_b32 m0, s66
	s_addc_u32 s11, s53, 0
	s_add_i32 s67, s65, 0x4000
	global_load_lds_dwordx4 v136, s[52:53]
	s_mov_b32 m0, s67
	s_add_i32 s79, s65, 0x6000
	global_load_lds_dwordx4 v132, s[10:11]
	s_mov_b32 m0, s79
	v_writelane_b32 v238, s94, 4
	global_load_lds_dwordx4 v136, s[10:11]
	v_mov_b32_e32 v135, 0
	v_writelane_b32 v238, s95, 5
	v_mov_b32_e32 v139, v135
	v_mov_b32_e32 v133, v135
	v_mov_b32_e32 v137, v135
	s_cmp_eq_u32 s7, 1
	v_writelane_b32 v238, s92, 6
	s_mov_b32 s11, 0
	v_lshl_add_u64 v[6:7], s[54:55], 0, v[134:135]
	v_lshl_add_u64 v[4:5], s[54:55], 0, v[138:139]
	v_lshl_add_u64 v[0:1], s[52:53], 0, v[132:133]
	s_cselect_b64 s[22:23], -1, 0
	v_lshl_add_u64 v[2:3], s[52:53], 0, v[136:137]
	v_writelane_b32 v238, s93, 7
	s_add_u32 s81, s70, 0x1f900000
	s_mov_b64 s[26:27], 0x80
	s_addc_u32 s82, s71, 0
	s_and_b32 s1, s4, 3
	s_add_i32 m0, s65, 0x18000
	v_lshl_add_u64 v[6:7], v[6:7], 0, s[26:27]
	s_lshl_b32 s9, s7, 13
	s_lshl_b32 s10, s1, 12
	global_load_lds_dwordx4 v[6:7], off
	v_lshl_add_u64 v[4:5], v[4:5], 0, s[26:27]
	s_add_i32 m0, s65, 0x1a000
	s_add_i32 s83, s65, 0x8000
	s_add_i32 s84, s65, 0xa000
	global_load_lds_dwordx4 v[4:5], off
	v_lshl_add_u64 v[0:1], v[0:1], 0, s[26:27]
	s_mov_b32 m0, s83
	s_add_u32 s4, s54, 0x40080
	global_load_lds_dwordx4 v[0:1], off
	v_lshl_add_u64 v[0:1], v[2:3], 0, s[26:27]
	s_mov_b32 m0, s84
	s_addc_u32 s5, s55, 0
	global_load_lds_dwordx4 v[0:1], off
	s_add_i32 m0, s65, 0x1c000
	v_lshl_add_u64 v[0:1], s[4:5], 0, v[134:135]
	global_load_lds_dwordx4 v[0:1], off
	v_lshl_add_u64 v[0:1], s[4:5], 0, v[138:139]
	s_add_i32 m0, s65, 0x1e000
	global_load_lds_dwordx4 v[0:1], off
	v_and_b32_e32 v114, 0xff, v128
	s_lshr_b32 s98, s91, 2
	v_mov_b32_e32 v115, 0x358637bd
	s_mul_i32 s99, s98, s72
	s_add_i32 s99, s99, s2
	s_cmp_lt_u32 s99, 0x600
	s_cselect_b32 s99, s99, s2
	s_and_b32 s100, s99, 7
	s_mul_i32 s100, s100, 0xc0
	s_lshr_b32 s101, s99, 3
	s_add_i32 s100, s100, s101
	s_mul_hi_u32 s101, s100, 0x2aaaaab
	s_lshl_b32 s101, s101, 3
	s_and_b32 s100, s100, 7
	s_or_b32 s101, s101, s100
	s_lshl_b32 s101, s101, 8
	v_add_u32_e32 v112, s101, v114
	v_lshlrev_b32_e32 v112, 6, v112
	v_mov_b32_e32 v113, 0
	v_lshl_add_u64 v[112:113], s[18:19], 0, v[112:113]
	global_load_dwordx4 v[16:19], v[112:113], off
	global_load_dwordx4 v[20:23], v[112:113], off offset:16
	global_load_dwordx4 v[24:27], v[112:113], off offset:32
	global_load_dwordx4 v[28:31], v[112:113], off offset:48
	s_add_i32 s98, s98, 2
	s_mul_i32 s99, s98, s72
	s_add_i32 s99, s99, s2
	s_cmp_lt_u32 s99, 0x600
	s_cselect_b32 s99, s99, s2
	s_and_b32 s100, s99, 7
	s_mul_i32 s100, s100, 0xc0
	s_lshr_b32 s101, s99, 3
	s_add_i32 s100, s100, s101
	s_mul_hi_u32 s101, s100, 0x2aaaaab
	s_lshl_b32 s101, s101, 3
	s_and_b32 s100, s100, 7
	s_or_b32 s101, s101, s100
	s_lshl_b32 s101, s101, 8
	v_add_u32_e32 v112, s101, v114
	v_lshlrev_b32_e32 v112, 6, v112
	v_mov_b32_e32 v113, 0
	v_lshl_add_u64 v[112:113], s[18:19], 0, v[112:113]
	global_load_dwordx4 v[32:35], v[112:113], off
	global_load_dwordx4 v[36:39], v[112:113], off offset:16
	global_load_dwordx4 v[40:43], v[112:113], off offset:32
	global_load_dwordx4 v[44:47], v[112:113], off offset:48
	s_add_i32 s98, s98, 2
	s_mul_i32 s99, s98, s72
	s_add_i32 s99, s99, s2
	s_cmp_lt_u32 s99, 0x600
	s_cselect_b32 s99, s99, s2
	s_and_b32 s100, s99, 7
	s_mul_i32 s100, s100, 0xc0
	s_lshr_b32 s101, s99, 3
	s_add_i32 s100, s100, s101
	s_mul_hi_u32 s101, s100, 0x2aaaaab
	s_lshl_b32 s101, s101, 3
	s_and_b32 s100, s100, 7
	s_or_b32 s101, s101, s100
	s_lshl_b32 s101, s101, 8
	v_add_u32_e32 v112, s101, v114
	v_lshlrev_b32_e32 v112, 6, v112
	v_mov_b32_e32 v113, 0
	v_lshl_add_u64 v[112:113], s[18:19], 0, v[112:113]
	global_load_dwordx4 v[48:51], v[112:113], off
	global_load_dwordx4 v[52:55], v[112:113], off offset:16
	global_load_dwordx4 v[56:59], v[112:113], off offset:32
	global_load_dwordx4 v[60:63], v[112:113], off offset:48
	s_add_i32 s98, s98, 2
	v_lshlrev_b32_e32 v116, 2, v128
	v_add_u32_e32 v116, 0x20000, v116
	s_waitcnt vmcnt(8)
	v_pk_add_f32 v[118:119], v[18:19], v[22:23]
	v_pk_add_f32 v[120:121], v[16:17], v[20:21]
	v_pk_add_f32 v[122:123], v[26:27], v[30:31]
	v_pk_add_f32 v[124:125], v[24:25], v[28:29]
	v_pk_add_f32 v[118:119], v[118:119], v[122:123]
	v_pk_add_f32 v[120:121], v[120:121], v[124:125]
	v_add_f32_e32 v120, v121, v120
	v_add_f32_e32 v118, v118, v119
	v_add_f32_e32 v118, v120, v118
	v_fmamk_f32 v118, v118, 0x3a800000, v115
	v_rsq_f32_e32 v118, v118
	ds_write_b32 v116, v118
	s_waitcnt vmcnt(4)
	v_pk_add_f32 v[118:119], v[34:35], v[38:39]
	v_pk_add_f32 v[120:121], v[32:33], v[36:37]
	v_pk_add_f32 v[122:123], v[42:43], v[46:47]
	v_pk_add_f32 v[124:125], v[40:41], v[44:45]
	v_pk_add_f32 v[118:119], v[118:119], v[122:123]
	v_pk_add_f32 v[120:121], v[120:121], v[124:125]
	v_add_f32_e32 v120, v121, v120
	v_add_f32_e32 v118, v118, v119
	v_add_f32_e32 v118, v120, v118
	v_fmamk_f32 v118, v118, 0x3a800000, v115
	v_rsq_f32_e32 v118, v118
	ds_write_b32 v116, v118 offset:2048
	s_waitcnt vmcnt(0)
	v_pk_add_f32 v[118:119], v[50:51], v[54:55]
	v_pk_add_f32 v[120:121], v[48:49], v[52:53]
	v_pk_add_f32 v[122:123], v[58:59], v[62:63]
	v_pk_add_f32 v[124:125], v[56:57], v[60:61]
	v_pk_add_f32 v[118:119], v[118:119], v[122:123]
	v_pk_add_f32 v[120:121], v[120:121], v[124:125]
	v_add_f32_e32 v120, v121, v120
	v_add_f32_e32 v118, v118, v119
	v_add_f32_e32 v118, v120, v118
	v_fmamk_f32 v118, v118, 0x3a800000, v115
	v_rsq_f32_e32 v118, v118
	ds_write_b32 v116, v118 offset:4096
	s_cmp_lg_u32 s7, 1
	s_cbranch_scc1 .LBB0_649
	s_barrier
.LBB0_649:
	s_waitcnt vmcnt(8) lgkmcnt(0)
	s_barrier
	s_cmpk_lt_u32 s6, 0x100
	v_bfe_u32 v1, v128, 4, 2
	v_and_b32_e32 v0, 15, v128
	v_lshlrev_b32_e32 v3, 4, v1
	s_cselect_b64 s[28:29], -1, 0
	s_lshl_b32 s6, s7, 8
	v_lshl_or_b32 v131, s7, 6, v0
	v_lshl_or_b32 v4, v0, 6, v3
	v_lshlrev_b32_e32 v0, 2, v0
	s_add_i32 s6, s6, 0
	v_and_b32_e32 v5, 32, v0
	s_add_i32 s6, s6, 0x20000
	v_bitop3_b32 v4, v4, s9, v5 bitop3:0xde
	v_lshlrev_b32_e32 v5, 6, v128
	s_movk_i32 s4, 0x3c0
	v_add_u32_e32 v159, s6, v0
	v_lshlrev_b32_e32 v0, 8, v128
	v_lshlrev_b32_e32 v2, 3, v1
	v_and_or_b32 v3, v5, s4, v3
	v_cmp_eq_u32_e64 s[4:5], 0, v1
	v_and_b32_e32 v0, 0x38000, v0
	v_lshlrev_b32_e32 v1, 11, v11
	v_or3_b32 v0, v9, v0, v1
	v_add_u32_e32 v140, v0, v10
	v_lshlrev_b32_e32 v0, 4, v12
	v_and_b32_e32 v0, 0x78000, v0
	v_and_b32_e32 v5, 32, v8
	s_waitcnt vmcnt(6)
	v_or3_b32 v0, v9, v0, v1
	v_bitop3_b32 v157, s10, v3, v5 bitop3:0xf6
	v_lshl_or_b32 v158, s1, 5, v2
	s_lshl_b32 s1, s1, 15
	v_add_u32_e32 v142, v0, v10
	s_add_i32 s88, 0, 0x10000
	s_add_i32 s89, 0, 0x14000
	v_mbcnt_lo_u32_b32 v0, -1, 0
	s_or_b32 s85, s1, 0xfff00000
	s_or_b32 s86, s1, 0xfff20000
	v_mov_b32_e32 v141, v135
	v_mov_b32_e32 v143, v135
	v_mov_b64_e32 v[144:145], 0x600
	v_mov_b64_e32 v[146:147], 0x5ff
	s_movk_i32 s87, 0xc1
	v_add_u32_e32 v160, s88, v157
	v_add_u32_e32 v161, s89, v157
	v_add_u32_e32 v162, 0, v4
	s_movk_i32 s92, 0x1800
	v_mbcnt_hi_u32_b32 v163, -1, v0
	s_mov_b32 s1, 0
	s_mov_b32 s93, 0
	s_barrier
	s_branch .LBB0_652

.LBB0_1050:
	s_or_b64 exec, exec, s[0:1]
	s_cmpk_gt_i32 s2, 0xaff
	v_readfirstlane_b32 s5, v128
	s_cbranch_scc1 .LBB0_1066
	v_lshrrev_b32_e32 v0, 5, v128
	v_lshrrev_b32_e32 v2, 1, v128
	v_and_b32_e32 v0, 4, v0
	v_bfe_u32 v1, v128, 2, 2
	v_and_b32_e32 v12, 24, v2
	v_or3_b32 v0, v0, v1, v12
	v_lshlrev_b32_e32 v1, 4, v128
	v_add_u32_e32 v9, 0x2000, v1
	v_lshrrev_b32_e32 v2, 7, v9
	s_movk_i32 s0, 0xe0
	v_and_b32_e32 v4, 32, v128
	v_and_or_b32 v3, v2, s0, v0
	v_bitop3_b32 v10, v1, v4, 48 bitop3:0x6c
	v_and_b32_e32 v11, 64, v128
	v_bfe_u32 v13, v128, 2, 4
	s_movk_i32 s0, 0xf0
	s_lshr_b32 s6, s5, 6
	v_or_b32_e32 v1, v10, v11
	v_and_or_b32 v2, v2, s0, v13
	s_lshr_b32 s10, s5, 8
	s_lshl_b32 s48, s6, 10
	v_lshl_or_b32 v134, v2, 11, v1
	v_lshrrev_b32_e32 v2, 3, v128
	s_movk_i32 s0, 0x60
	s_add_u32 s49, s70, 0x2180000
	v_and_or_b32 v0, v2, s0, v0
	s_movk_i32 s0, 0x70
	s_addc_u32 s50, s71, 0
	v_lshl_or_b32 v136, v0, 11, v1
	v_and_or_b32 v0, v2, s0, v13
	s_lshr_b32 s0, s3, 29
	s_add_i32 s0, s2, s0
	s_ashr_i32 s1, s0, 3
	s_and_b32 s0, s0, -8
	s_sub_i32 s0, s2, s0
	s_cmp_lt_i32 s0, 0
	s_movk_i32 s51, 0x161
	s_cselect_b32 s4, s51, 0x160
	s_mul_i32 s0, s0, s4
	s_add_i32 s0, s0, s1
	s_mul_hi_i32 s1, s0, 0x2e8ba2e9
	s_lshr_b32 s4, s1, 31
	s_ashr_i32 s1, s1, 5
	s_add_i32 s1, s1, s4
	s_lshl_b32 s7, s1, 3
	s_mulk_i32 s1, 0xb0
	s_sub_i32 s0, s0, s1
	s_bfe_u32 s1, s0, 0x3001c
	s_add_i32 s1, s0, s1
	s_sext_i32_i16 s4, s1
	s_and_b32 s1, s1, 0xfff8
	s_sub_i32 s0, s0, s1
	s_sext_i32_i16 s0, s0
	s_lshr_b32 s4, s4, 3
	s_add_i32 s30, s7, s0
	s_ashr_i32 s31, s30, 31
	s_bfe_i64 s[8:9], s[4:5], 0x100000
	s_lshl_b64 s[0:1], s[30:31], 19
	s_lshl_b64 s[8:9], s[8:9], 19
	s_add_u32 s38, s49, s8
	s_addc_u32 s39, s50, s9
	s_add_i32 s31, s48, 0
	s_add_i32 m0, s31, 0x10000
	v_lshl_or_b32 v132, v3, 11, v1
	global_load_lds_dwordx4 v136, s[38:39]
	s_add_i32 m0, s31, 0x12000
	s_add_u32 s8, s38, 0x40000
	global_load_lds_dwordx4 v132, s[38:39]
	s_addc_u32 s9, s39, 0
	s_add_i32 m0, s31, 0x14000
	v_lshl_or_b32 v138, v0, 11, v1
	global_load_lds_dwordx4 v136, s[8:9]
	s_add_i32 m0, s31, 0x16000
	s_add_u32 s36, s14, s0
	s_addc_u32 s37, s15, s1
	s_add_i32 s52, s31, 0x2000
	global_load_lds_dwordx4 v132, s[8:9]
	s_mov_b32 m0, s31
	s_add_u32 s0, s36, 0x40000
	global_load_lds_dwordx4 v138, s[36:37]
	s_mov_b32 m0, s52
	s_addc_u32 s1, s37, 0
	s_add_i32 s53, s31, 0x4000
	global_load_lds_dwordx4 v134, s[36:37]
	s_mov_b32 m0, s53
	s_add_i32 s54, s31, 0x6000
	global_load_lds_dwordx4 v138, s[0:1]
	s_mov_b32 m0, s54
	v_mov_b32_e32 v137, 0
	global_load_lds_dwordx4 v134, s[0:1]
	v_mov_b32_e32 v133, v137
	v_mov_b32_e32 v139, v137
	v_mov_b32_e32 v135, v137
	s_cmp_eq_u32 s10, 1
	s_mov_b32 s12, 0
	v_lshl_add_u64 v[6:7], s[38:39], 0, v[136:137]
	v_lshl_add_u64 v[4:5], s[38:39], 0, v[132:133]
	v_lshl_add_u64 v[0:1], s[36:37], 0, v[138:139]
	s_cselect_b64 s[0:1], -1, 0
	v_lshl_add_u64 v[2:3], s[36:37], 0, v[134:135]
	s_lshl_b32 s6, s6, 5
	s_and_b32 s22, s6, 0x60
	s_mov_b64 s[6:7], 0x80
	s_add_i32 m0, s31, 0x18000
	v_lshl_add_u64 v[6:7], v[6:7], 0, s[6:7]
	s_lshl_b32 s11, s10, 13
	s_lshl_b32 s23, s22, 7
	global_load_lds_dwordx4 v[6:7], off
	v_lshl_add_u64 v[4:5], v[4:5], 0, s[6:7]
	s_add_i32 m0, s31, 0x1a000
	s_add_i32 s55, s31, 0x8000
	s_add_i32 s56, s31, 0xa000
	global_load_lds_dwordx4 v[4:5], off
	v_lshl_add_u64 v[0:1], v[0:1], 0, s[6:7]
	s_mov_b32 m0, s55
	s_add_u32 s8, s38, 0x40080
	global_load_lds_dwordx4 v[0:1], off
	v_lshl_add_u64 v[0:1], v[2:3], 0, s[6:7]
	s_mov_b32 m0, s56
	s_addc_u32 s9, s39, 0
	global_load_lds_dwordx4 v[0:1], off
	s_add_i32 m0, s31, 0x1c000
	v_lshl_add_u64 v[0:1], s[8:9], 0, v[136:137]
	global_load_lds_dwordx4 v[0:1], off
	v_lshl_add_u64 v[0:1], s[8:9], 0, v[132:133]
	s_add_i32 m0, s31, 0x1e000
	s_sext_i32_i16 s13, s4
	global_load_lds_dwordx4 v[0:1], off
	v_and_b32_e32 v114, 0xff, v128
	s_lshr_b32 s98, s91, 2
	v_mov_b32_e32 v115, 0x358637bd
	s_mul_i32 s99, s98, s72
	s_add_i32 s99, s99, s2
	s_cmp_lt_u32 s99, 0xb00
	s_cselect_b32 s99, s99, s2
	s_and_b32 s100, s99, 7
	s_mul_i32 s100, s100, 0x160
	s_lshr_b32 s101, s99, 3
	s_add_i32 s100, s100, s101
	s_mul_hi_u32 s101, s100, 0x1745d18
	s_lshl_b32 s101, s101, 3
	s_and_b32 s100, s100, 7
	s_or_b32 s101, s101, s100
	s_lshl_b32 s101, s101, 8
	v_add_u32_e32 v112, s101, v114
	v_lshlrev_b32_e32 v112, 6, v112
	v_mov_b32_e32 v113, 0
	v_lshl_add_u64 v[112:113], s[18:19], 0, v[112:113]
	global_load_dwordx4 v[16:19], v[112:113], off
	global_load_dwordx4 v[20:23], v[112:113], off offset:16
	global_load_dwordx4 v[24:27], v[112:113], off offset:32
	global_load_dwordx4 v[28:31], v[112:113], off offset:48
	s_add_i32 s98, s98, 2
	s_mul_i32 s99, s98, s72
	s_add_i32 s99, s99, s2
	s_cmp_lt_u32 s99, 0xb00
	s_cselect_b32 s99, s99, s2
	s_and_b32 s100, s99, 7
	s_mul_i32 s100, s100, 0x160
	s_lshr_b32 s101, s99, 3
	s_add_i32 s100, s100, s101
	s_mul_hi_u32 s101, s100, 0x1745d18
	s_lshl_b32 s101, s101, 3
	s_and_b32 s100, s100, 7
	s_or_b32 s101, s101, s100
	s_lshl_b32 s101, s101, 8
	v_add_u32_e32 v112, s101, v114
	v_lshlrev_b32_e32 v112, 6, v112
	v_mov_b32_e32 v113, 0
	v_lshl_add_u64 v[112:113], s[18:19], 0, v[112:113]
	global_load_dwordx4 v[32:35], v[112:113], off
	global_load_dwordx4 v[36:39], v[112:113], off offset:16
	global_load_dwordx4 v[40:43], v[112:113], off offset:32
	global_load_dwordx4 v[44:47], v[112:113], off offset:48
	s_add_i32 s98, s98, 2
	s_mul_i32 s99, s98, s72
	s_add_i32 s99, s99, s2
	s_cmp_lt_u32 s99, 0xb00
	s_cselect_b32 s99, s99, s2
	s_and_b32 s100, s99, 7
	s_mul_i32 s100, s100, 0x160
	s_lshr_b32 s101, s99, 3
	s_add_i32 s100, s100, s101
	s_mul_hi_u32 s101, s100, 0x1745d18
	s_lshl_b32 s101, s101, 3
	s_and_b32 s100, s100, 7
	s_or_b32 s101, s101, s100
	s_lshl_b32 s101, s101, 8
	v_add_u32_e32 v112, s101, v114
	v_lshlrev_b32_e32 v112, 6, v112
	v_mov_b32_e32 v113, 0
	v_lshl_add_u64 v[112:113], s[18:19], 0, v[112:113]
	global_load_dwordx4 v[48:51], v[112:113], off
	global_load_dwordx4 v[52:55], v[112:113], off offset:16
	global_load_dwordx4 v[56:59], v[112:113], off offset:32
	global_load_dwordx4 v[60:63], v[112:113], off offset:48
	s_add_i32 s98, s98, 2
	s_mul_i32 s99, s98, s72
	s_add_i32 s99, s99, s2
	s_cmp_lt_u32 s99, 0xb00
	s_cselect_b32 s99, s99, s2
	s_and_b32 s100, s99, 7
	s_mul_i32 s100, s100, 0x160
	s_lshr_b32 s101, s99, 3
	s_add_i32 s100, s100, s101
	s_mul_hi_u32 s101, s100, 0x1745d18
	s_lshl_b32 s101, s101, 3
	s_and_b32 s100, s100, 7
	s_or_b32 s101, s101, s100
	s_lshl_b32 s101, s101, 8
	v_add_u32_e32 v112, s101, v114
	v_lshlrev_b32_e32 v112, 6, v112
	v_mov_b32_e32 v113, 0
	v_lshl_add_u64 v[112:113], s[18:19], 0, v[112:113]
	global_load_dwordx4 v[64:67], v[112:113], off
	global_load_dwordx4 v[68:71], v[112:113], off offset:16
	global_load_dwordx4 v[72:75], v[112:113], off offset:32
	global_load_dwordx4 v[76:79], v[112:113], off offset:48
	s_add_i32 s98, s98, 2
	s_mul_i32 s99, s98, s72
	s_add_i32 s99, s99, s2
	s_cmp_lt_u32 s99, 0xb00
	s_cselect_b32 s99, s99, s2
	s_and_b32 s100, s99, 7
	s_mul_i32 s100, s100, 0x160
	s_lshr_b32 s101, s99, 3
	s_add_i32 s100, s100, s101
	s_mul_hi_u32 s101, s100, 0x1745d18
	s_lshl_b32 s101, s101, 3
	s_and_b32 s100, s100, 7
	s_or_b32 s101, s101, s100
	s_lshl_b32 s101, s101, 8
	v_add_u32_e32 v112, s101, v114
	v_lshlrev_b32_e32 v112, 6, v112
	v_mov_b32_e32 v113, 0
	v_lshl_add_u64 v[112:113], s[18:19], 0, v[112:113]
	global_load_dwordx4 v[80:83], v[112:113], off
	global_load_dwordx4 v[84:87], v[112:113], off offset:16
	global_load_dwordx4 v[88:91], v[112:113], off offset:32
	global_load_dwordx4 v[92:95], v[112:113], off offset:48
	s_add_i32 s98, s98, 2
	s_mul_i32 s99, s98, s72
	s_add_i32 s99, s99, s2
	s_cmp_lt_u32 s99, 0xb00
	s_cselect_b32 s99, s99, s2
	s_and_b32 s100, s99, 7
	s_mul_i32 s100, s100, 0x160
	s_lshr_b32 s101, s99, 3
	s_add_i32 s100, s100, s101
	s_mul_hi_u32 s101, s100, 0x1745d18
	s_lshl_b32 s101, s101, 3
	s_and_b32 s100, s100, 7
	s_or_b32 s101, s101, s100
	s_lshl_b32 s101, s101, 8
	v_add_u32_e32 v112, s101, v114
	v_lshlrev_b32_e32 v112, 6, v112
	v_mov_b32_e32 v113, 0
	v_lshl_add_u64 v[112:113], s[18:19], 0, v[112:113]
	global_load_dwordx4 v[96:99], v[112:113], off
	global_load_dwordx4 v[100:103], v[112:113], off offset:16
	global_load_dwordx4 v[104:107], v[112:113], off offset:32
	global_load_dwordx4 v[108:111], v[112:113], off offset:48
	s_add_i32 s98, s98, 2
	v_lshlrev_b32_e32 v116, 2, v128
	v_add_u32_e32 v116, 0x20000, v116
	s_waitcnt vmcnt(20)
	v_pk_add_f32 v[118:119], v[18:19], v[22:23]
	v_pk_add_f32 v[120:121], v[16:17], v[20:21]
	v_pk_add_f32 v[122:123], v[26:27], v[30:31]
	v_pk_add_f32 v[124:125], v[24:25], v[28:29]
	v_pk_add_f32 v[118:119], v[118:119], v[122:123]
	v_pk_add_f32 v[120:121], v[120:121], v[124:125]
	v_add_f32_e32 v120, v121, v120
	v_add_f32_e32 v118, v118, v119
	v_add_f32_e32 v118, v120, v118
	v_fmamk_f32 v118, v118, 0x3a800000, v115
	v_rsq_f32_e32 v118, v118
	ds_write_b32 v116, v118
	s_waitcnt vmcnt(16)
	v_pk_add_f32 v[118:119], v[34:35], v[38:39]
	v_pk_add_f32 v[120:121], v[32:33], v[36:37]
	v_pk_add_f32 v[122:123], v[42:43], v[46:47]
	v_pk_add_f32 v[124:125], v[40:41], v[44:45]
	v_pk_add_f32 v[118:119], v[118:119], v[122:123]
	v_pk_add_f32 v[120:121], v[120:121], v[124:125]
	v_add_f32_e32 v120, v121, v120
	v_add_f32_e32 v118, v118, v119
	v_add_f32_e32 v118, v120, v118
	v_fmamk_f32 v118, v118, 0x3a800000, v115
	v_rsq_f32_e32 v118, v118
	ds_write_b32 v116, v118 offset:2048
	s_waitcnt vmcnt(12)
	v_pk_add_f32 v[118:119], v[50:51], v[54:55]
	v_pk_add_f32 v[120:121], v[48:49], v[52:53]
	v_pk_add_f32 v[122:123], v[58:59], v[62:63]
	v_pk_add_f32 v[124:125], v[56:57], v[60:61]
	v_pk_add_f32 v[118:119], v[118:119], v[122:123]
	v_pk_add_f32 v[120:121], v[120:121], v[124:125]
	v_add_f32_e32 v120, v121, v120
	v_add_f32_e32 v118, v118, v119
	v_add_f32_e32 v118, v120, v118
	v_fmamk_f32 v118, v118, 0x3a800000, v115
	v_rsq_f32_e32 v118, v118
	ds_write_b32 v116, v118 offset:4096
	s_waitcnt vmcnt(8)
	v_pk_add_f32 v[118:119], v[66:67], v[70:71]
	v_pk_add_f32 v[120:121], v[64:65], v[68:69]
	v_pk_add_f32 v[122:123], v[74:75], v[78:79]
	v_pk_add_f32 v[124:125], v[72:73], v[76:77]
	v_pk_add_f32 v[118:119], v[118:119], v[122:123]
	v_pk_add_f32 v[120:121], v[120:121], v[124:125]
	v_add_f32_e32 v120, v121, v120
	v_add_f32_e32 v118, v118, v119
	v_add_f32_e32 v118, v120, v118
	v_fmamk_f32 v118, v118, 0x3a800000, v115
	v_rsq_f32_e32 v118, v118
	ds_write_b32 v116, v118 offset:6144
	s_waitcnt vmcnt(4)
	v_pk_add_f32 v[118:119], v[82:83], v[86:87]
	v_pk_add_f32 v[120:121], v[80:81], v[84:85]
	v_pk_add_f32 v[122:123], v[90:91], v[94:95]
	v_pk_add_f32 v[124:125], v[88:89], v[92:93]
	v_pk_add_f32 v[118:119], v[118:119], v[122:123]
	v_pk_add_f32 v[120:121], v[120:121], v[124:125]
	v_add_f32_e32 v120, v121, v120
	v_add_f32_e32 v118, v118, v119
	v_add_f32_e32 v118, v120, v118
	v_fmamk_f32 v118, v118, 0x3a800000, v115
	v_rsq_f32_e32 v118, v118
	ds_write_b32 v116, v118 offset:8192
	s_waitcnt vmcnt(0)
	v_pk_add_f32 v[118:119], v[98:99], v[102:103]
	v_pk_add_f32 v[120:121], v[96:97], v[100:101]
	v_pk_add_f32 v[122:123], v[106:107], v[110:111]
	v_pk_add_f32 v[124:125], v[104:105], v[108:109]
	v_pk_add_f32 v[118:119], v[118:119], v[122:123]
	v_pk_add_f32 v[120:121], v[120:121], v[124:125]
	v_add_f32_e32 v120, v121, v120
	v_add_f32_e32 v118, v118, v119
	v_add_f32_e32 v118, v120, v118
	v_fmamk_f32 v118, v118, 0x3a800000, v115
	v_rsq_f32_e32 v118, v118
	ds_write_b32 v116, v118 offset:10240
	s_cmp_lg_u32 s10, 1
	s_cbranch_scc1 .LBB0_1053
	s_barrier
.LBB0_1053:
	s_waitcnt vmcnt(8) lgkmcnt(0)
	s_barrier
	v_and_b32_e32 v0, 15, v128
	v_lshlrev_b32_e32 v1, 1, v12
	v_lshl_or_b32 v131, s10, 6, v0
	v_lshl_or_b32 v2, v0, 6, v1
	v_lshlrev_b32_e32 v0, 2, v0
	v_and_b32_e32 v3, 32, v0
	v_bitop3_b32 v2, v2, s11, v3 bitop3:0xde
	v_lshlrev_b32_e32 v3, 6, v128
	s_movk_i32 s4, 0x3c0
	s_cmpk_lt_u32 s5, 0x100
	v_and_or_b32 v1, v3, s4, v1
	s_cselect_b64 s[8:9], -1, 0
	s_lshl_b32 s4, s10, 8
	s_add_i32 s4, s4, 0
	s_add_i32 s4, s4, 0x20000
	v_and_b32_e32 v3, 32, v8
	v_add_u32_e32 v153, s4, v0
	v_lshlrev_b32_e32 v0, 8, v128
	v_bitop3_b32 v152, s23, v1, v3 bitop3:0xf6
	v_and_b32_e32 v0, 0x38000, v0
	v_lshlrev_b32_e32 v1, 11, v13
	v_or3_b32 v0, v10, v0, v1
	v_add_u32_e32 v140, v0, v11
	v_lshlrev_b32_e32 v0, 4, v9
	s_waitcnt vmcnt(6)
	v_and_b32_e32 v0, 0x78000, v0
	v_or3_b32 v0, v10, v0, v1
	s_add_i32 s57, 0, 0x10000
	s_add_i32 s58, 0, 0x14000
	v_or_b32_e32 v154, s22, v12
	v_mov_b32_e32 v141, v137
	v_add_u32_e32 v142, v0, v11
	v_mov_b32_e32 v143, v137
	v_mov_b64_e32 v[144:145], 0xb00
	v_mov_b64_e32 v[146:147], 0xaff
	v_add_u32_e32 v155, s57, v152
	v_add_u32_e32 v157, s58, v152
	v_add_u32_e32 v158, 0, v2
	s_movk_i32 s59, 0x1600
	s_mov_b32 s62, 0
	s_barrier
	s_branch .LBB0_1056

.LBB0_1226:
	s_or_b64 exec, exec, s[0:1]
	s_cmpk_gt_i32 s2, 0x5ff
	v_readfirstlane_b32 s5, v128
	s_cbranch_scc1 .LBB0_1242
	v_lshrrev_b32_e32 v0, 5, v128
	v_lshrrev_b32_e32 v2, 1, v128
	v_and_b32_e32 v0, 4, v0
	v_bfe_u32 v1, v128, 2, 2
	v_and_b32_e32 v12, 24, v2
	v_or3_b32 v0, v0, v1, v12
	v_lshlrev_b32_e32 v1, 4, v128
	v_add_u32_e32 v9, 0x2000, v1
	v_lshrrev_b32_e32 v2, 7, v9
	s_movk_i32 s0, 0xe0
	v_and_b32_e32 v4, 32, v128
	v_and_or_b32 v3, v2, s0, v0
	v_bitop3_b32 v10, v1, v4, 48 bitop3:0x6c
	v_and_b32_e32 v11, 64, v128
	v_bfe_u32 v13, v128, 2, 4
	s_movk_i32 s0, 0xf0
	s_lshr_b32 s6, s5, 6
	v_or_b32_e32 v1, v10, v11
	v_and_or_b32 v2, v2, s0, v13
	s_lshr_b32 s10, s5, 8
	s_lshl_b32 s48, s6, 10
	v_lshl_or_b32 v134, v2, 11, v1
	v_lshrrev_b32_e32 v2, 3, v128
	s_movk_i32 s0, 0x60
	s_add_u32 s49, s70, 0x3200000
	v_and_or_b32 v0, v2, s0, v0
	s_movk_i32 s0, 0x70
	s_addc_u32 s50, s71, 0
	v_lshl_or_b32 v136, v0, 11, v1
	v_and_or_b32 v0, v2, s0, v13
	s_lshr_b32 s0, s3, 29
	s_add_i32 s0, s2, s0
	s_ashr_i32 s1, s0, 3
	s_and_b32 s0, s0, -8
	s_sub_i32 s0, s2, s0
	s_cmp_lt_i32 s0, 0
	s_movk_i32 s51, 0xc1
	s_cselect_b32 s4, s51, 0xc0
	s_mul_i32 s0, s0, s4
	s_add_i32 s0, s0, s1
	s_mul_hi_i32 s1, s0, 0x2aaaaaab
	s_lshr_b32 s4, s1, 31
	s_ashr_i32 s1, s1, 4
	s_add_i32 s1, s1, s4
	s_lshl_b32 s7, s1, 3
	s_mulk_i32 s1, 0x60
	s_sub_i32 s0, s0, s1
	s_bfe_i32 s1, s0, 0x80000
	s_bfe_u32 s1, s1, 0x3000c
	s_add_i32 s1, s0, s1
	s_bfe_i32 s4, s1, 0x80000
	s_and_b32 s1, s1, 0xf8
	s_sub_i32 s0, s0, s1
	s_sext_i32_i16 s4, s4
	s_sext_i32_i8 s0, s0
	s_lshr_b32 s4, s4, 3
	s_add_i32 s30, s7, s0
	s_ashr_i32 s31, s30, 31
	s_bfe_i64 s[8:9], s[4:5], 0x100000
	s_lshl_b64 s[0:1], s[30:31], 19
	s_lshl_b64 s[8:9], s[8:9], 19
	s_add_u32 s38, s49, s8
	s_addc_u32 s39, s50, s9
	s_add_i32 s31, s48, 0
	s_add_i32 m0, s31, 0x10000
	v_lshl_or_b32 v132, v3, 11, v1
	global_load_lds_dwordx4 v136, s[38:39]
	s_add_i32 m0, s31, 0x12000
	s_add_u32 s8, s38, 0x40000
	global_load_lds_dwordx4 v132, s[38:39]
	s_addc_u32 s9, s39, 0
	s_add_i32 m0, s31, 0x14000
	v_lshl_or_b32 v138, v0, 11, v1
	global_load_lds_dwordx4 v136, s[8:9]
	s_add_i32 m0, s31, 0x16000
	s_add_u32 s36, s14, s0
	s_addc_u32 s37, s15, s1
	s_add_i32 s52, s31, 0x2000
	global_load_lds_dwordx4 v132, s[8:9]
	s_mov_b32 m0, s31
	s_add_u32 s0, s36, 0x40000
	global_load_lds_dwordx4 v138, s[36:37]
	s_mov_b32 m0, s52
	s_addc_u32 s1, s37, 0
	s_add_i32 s53, s31, 0x4000
	global_load_lds_dwordx4 v134, s[36:37]
	s_mov_b32 m0, s53
	s_add_i32 s54, s31, 0x6000
	global_load_lds_dwordx4 v138, s[0:1]
	s_mov_b32 m0, s54
	v_mov_b32_e32 v137, 0
	global_load_lds_dwordx4 v134, s[0:1]
	v_mov_b32_e32 v133, v137
	v_mov_b32_e32 v139, v137
	v_mov_b32_e32 v135, v137
	s_cmp_eq_u32 s10, 1
	s_mov_b32 s62, 0
	v_lshl_add_u64 v[6:7], s[38:39], 0, v[136:137]
	v_lshl_add_u64 v[4:5], s[38:39], 0, v[132:133]
	v_lshl_add_u64 v[0:1], s[36:37], 0, v[138:139]
	s_cselect_b64 s[0:1], -1, 0
	v_lshl_add_u64 v[2:3], s[36:37], 0, v[134:135]
	s_lshl_b32 s6, s6, 5
	s_and_b32 s22, s6, 0x60
	s_mov_b64 s[6:7], 0x80
	s_add_i32 m0, s31, 0x18000
	v_lshl_add_u64 v[6:7], v[6:7], 0, s[6:7]
	s_lshl_b32 s11, s10, 13
	s_lshl_b32 s23, s22, 7
	global_load_lds_dwordx4 v[6:7], off
	v_lshl_add_u64 v[4:5], v[4:5], 0, s[6:7]
	s_add_i32 m0, s31, 0x1a000
	s_add_i32 s12, s31, 0x8000
	s_add_i32 s13, s31, 0xa000
	global_load_lds_dwordx4 v[4:5], off
	v_lshl_add_u64 v[0:1], v[0:1], 0, s[6:7]
	s_mov_b32 m0, s12
	s_add_u32 s8, s38, 0x40080
	global_load_lds_dwordx4 v[0:1], off
	v_lshl_add_u64 v[0:1], v[2:3], 0, s[6:7]
	s_mov_b32 m0, s13
	s_addc_u32 s9, s39, 0
	global_load_lds_dwordx4 v[0:1], off
	s_add_i32 m0, s31, 0x1c000
	v_lshl_add_u64 v[0:1], s[8:9], 0, v[136:137]
	global_load_lds_dwordx4 v[0:1], off
	v_lshl_add_u64 v[0:1], s[8:9], 0, v[132:133]
	s_add_i32 m0, s31, 0x1e000
	s_sext_i32_i8 s63, s4
	global_load_lds_dwordx4 v[0:1], off
	v_and_b32_e32 v114, 0xff, v128
	s_lshr_b32 s98, s91, 2
	v_mov_b32_e32 v115, 0x358637bd
	s_mul_i32 s99, s98, s72
	s_add_i32 s99, s99, s2
	s_cmp_lt_u32 s99, 0x600
	s_cselect_b32 s99, s99, s2
	s_and_b32 s100, s99, 7
	s_mul_i32 s100, s100, 0xc0
	s_lshr_b32 s101, s99, 3
	s_add_i32 s100, s100, s101
	s_mul_hi_u32 s101, s100, 0x2aaaaab
	s_lshl_b32 s101, s101, 3
	s_and_b32 s100, s100, 7
	s_or_b32 s101, s101, s100
	s_lshl_b32 s101, s101, 8
	v_add_u32_e32 v112, s101, v114
	v_lshlrev_b32_e32 v112, 6, v112
	v_mov_b32_e32 v113, 0
	v_lshl_add_u64 v[112:113], s[18:19], 0, v[112:113]
	global_load_dwordx4 v[16:19], v[112:113], off
	global_load_dwordx4 v[20:23], v[112:113], off offset:16
	global_load_dwordx4 v[24:27], v[112:113], off offset:32
	global_load_dwordx4 v[28:31], v[112:113], off offset:48
	s_add_i32 s98, s98, 2
	s_mul_i32 s99, s98, s72
	s_add_i32 s99, s99, s2
	s_cmp_lt_u32 s99, 0x600
	s_cselect_b32 s99, s99, s2
	s_and_b32 s100, s99, 7
	s_mul_i32 s100, s100, 0xc0
	s_lshr_b32 s101, s99, 3
	s_add_i32 s100, s100, s101
	s_mul_hi_u32 s101, s100, 0x2aaaaab
	s_lshl_b32 s101, s101, 3
	s_and_b32 s100, s100, 7
	s_or_b32 s101, s101, s100
	s_lshl_b32 s101, s101, 8
	v_add_u32_e32 v112, s101, v114
	v_lshlrev_b32_e32 v112, 6, v112
	v_mov_b32_e32 v113, 0
	v_lshl_add_u64 v[112:113], s[18:19], 0, v[112:113]
	global_load_dwordx4 v[32:35], v[112:113], off
	global_load_dwordx4 v[36:39], v[112:113], off offset:16
	global_load_dwordx4 v[40:43], v[112:113], off offset:32
	global_load_dwordx4 v[44:47], v[112:113], off offset:48
	s_add_i32 s98, s98, 2
	s_mul_i32 s99, s98, s72
	s_add_i32 s99, s99, s2
	s_cmp_lt_u32 s99, 0x600
	s_cselect_b32 s99, s99, s2
	s_and_b32 s100, s99, 7
	s_mul_i32 s100, s100, 0xc0
	s_lshr_b32 s101, s99, 3
	s_add_i32 s100, s100, s101
	s_mul_hi_u32 s101, s100, 0x2aaaaab
	s_lshl_b32 s101, s101, 3
	s_and_b32 s100, s100, 7
	s_or_b32 s101, s101, s100
	s_lshl_b32 s101, s101, 8
	v_add_u32_e32 v112, s101, v114
	v_lshlrev_b32_e32 v112, 6, v112
	v_mov_b32_e32 v113, 0
	v_lshl_add_u64 v[112:113], s[18:19], 0, v[112:113]
	global_load_dwordx4 v[48:51], v[112:113], off
	global_load_dwordx4 v[52:55], v[112:113], off offset:16
	global_load_dwordx4 v[56:59], v[112:113], off offset:32
	global_load_dwordx4 v[60:63], v[112:113], off offset:48
	s_add_i32 s98, s98, 2
	v_lshlrev_b32_e32 v116, 2, v128
	v_add_u32_e32 v116, 0x20000, v116
	s_waitcnt vmcnt(8)
	v_pk_add_f32 v[118:119], v[18:19], v[22:23]
	v_pk_add_f32 v[120:121], v[16:17], v[20:21]
	v_pk_add_f32 v[122:123], v[26:27], v[30:31]
	v_pk_add_f32 v[124:125], v[24:25], v[28:29]
	v_pk_add_f32 v[118:119], v[118:119], v[122:123]
	v_pk_add_f32 v[120:121], v[120:121], v[124:125]
	v_add_f32_e32 v120, v121, v120
	v_add_f32_e32 v118, v118, v119
	v_add_f32_e32 v118, v120, v118
	v_fmamk_f32 v118, v118, 0x3a800000, v115
	v_rsq_f32_e32 v118, v118
	ds_write_b32 v116, v118
	s_waitcnt vmcnt(4)
	v_pk_add_f32 v[118:119], v[34:35], v[38:39]
	v_pk_add_f32 v[120:121], v[32:33], v[36:37]
	v_pk_add_f32 v[122:123], v[42:43], v[46:47]
	v_pk_add_f32 v[124:125], v[40:41], v[44:45]
	v_pk_add_f32 v[118:119], v[118:119], v[122:123]
	v_pk_add_f32 v[120:121], v[120:121], v[124:125]
	v_add_f32_e32 v120, v121, v120
	v_add_f32_e32 v118, v118, v119
	v_add_f32_e32 v118, v120, v118
	v_fmamk_f32 v118, v118, 0x3a800000, v115
	v_rsq_f32_e32 v118, v118
	ds_write_b32 v116, v118 offset:2048
	s_waitcnt vmcnt(0)
	v_pk_add_f32 v[118:119], v[50:51], v[54:55]
	v_pk_add_f32 v[120:121], v[48:49], v[52:53]
	v_pk_add_f32 v[122:123], v[58:59], v[62:63]
	v_pk_add_f32 v[124:125], v[56:57], v[60:61]
	v_pk_add_f32 v[118:119], v[118:119], v[122:123]
	v_pk_add_f32 v[120:121], v[120:121], v[124:125]
	v_add_f32_e32 v120, v121, v120
	v_add_f32_e32 v118, v118, v119
	v_add_f32_e32 v118, v120, v118
	v_fmamk_f32 v118, v118, 0x3a800000, v115
	v_rsq_f32_e32 v118, v118
	ds_write_b32 v116, v118 offset:4096
	s_cmp_lg_u32 s10, 1
	s_cbranch_scc1 .LBB0_1229
	s_barrier
.LBB0_1229:
	s_waitcnt vmcnt(8) lgkmcnt(0)
	s_barrier
	v_and_b32_e32 v0, 15, v128
	v_lshlrev_b32_e32 v1, 1, v12
	v_lshl_or_b32 v131, s10, 6, v0
	v_lshl_or_b32 v2, v0, 6, v1
	v_lshlrev_b32_e32 v0, 2, v0
	v_and_b32_e32 v3, 32, v0
	v_bitop3_b32 v2, v2, s11, v3 bitop3:0xde
	v_lshlrev_b32_e32 v3, 6, v128
	s_movk_i32 s4, 0x3c0
	s_cmpk_lt_u32 s5, 0x100
	v_and_or_b32 v1, v3, s4, v1
	s_cselect_b64 s[8:9], -1, 0
	s_lshl_b32 s4, s10, 8
	s_add_i32 s4, s4, 0
	s_add_i32 s4, s4, 0x20000
	v_and_b32_e32 v3, 32, v8
	v_add_u32_e32 v153, s4, v0
	v_lshlrev_b32_e32 v0, 8, v128
	v_bitop3_b32 v152, s23, v1, v3 bitop3:0xf6
	v_and_b32_e32 v0, 0x38000, v0
	v_lshlrev_b32_e32 v1, 11, v13
	v_or3_b32 v0, v10, v0, v1
	v_add_u32_e32 v140, v0, v11
	v_lshlrev_b32_e32 v0, 4, v9
	s_waitcnt vmcnt(6)
	v_and_b32_e32 v0, 0x78000, v0
	v_or3_b32 v0, v10, v0, v1
	s_add_i32 s55, 0, 0x10000
	s_add_i32 s56, 0, 0x14000
	v_or_b32_e32 v154, s22, v12
	v_mov_b32_e32 v141, v137
	v_add_u32_e32 v142, v0, v11
	v_mov_b32_e32 v143, v137
	v_mov_b64_e32 v[144:145], 0x600
	v_mov_b64_e32 v[146:147], 0x5ff
	v_add_u32_e32 v155, s55, v152
	v_add_u32_e32 v157, s56, v152
	v_add_u32_e32 v158, 0, v2
	s_movk_i32 s57, 0x1800
	s_mov_b32 s58, 0
	s_barrier
	s_branch .LBB0_1232

.LBB0_1638:
	s_or_b64 exec, exec, s[0:1]
	s_cmpk_gt_i32 s2, 0xaff
	v_readfirstlane_b32 s5, v128
	s_cbranch_scc1 .LBB0_1654
	v_lshrrev_b32_e32 v0, 5, v128
	v_lshrrev_b32_e32 v2, 1, v128
	v_and_b32_e32 v0, 4, v0
	v_bfe_u32 v1, v128, 2, 2
	v_and_b32_e32 v12, 24, v2
	v_or3_b32 v0, v0, v1, v12
	v_lshlrev_b32_e32 v1, 4, v128
	v_add_u32_e32 v9, 0x2000, v1
	v_lshrrev_b32_e32 v2, 7, v9
	s_movk_i32 s0, 0xe0
	v_and_b32_e32 v4, 32, v128
	v_and_or_b32 v3, v2, s0, v0
	v_bitop3_b32 v10, v1, v4, 48 bitop3:0x6c
	v_and_b32_e32 v11, 64, v128
	v_bfe_u32 v13, v128, 2, 4
	s_movk_i32 s0, 0xf0
	s_lshr_b32 s6, s5, 6
	v_or_b32_e32 v1, v10, v11
	v_and_or_b32 v2, v2, s0, v13
	s_lshr_b32 s10, s5, 8
	s_lshl_b32 s44, s6, 10
	v_lshl_or_b32 v132, v2, 11, v1
	v_lshrrev_b32_e32 v2, 3, v128
	s_movk_i32 s0, 0x60
	s_add_u32 s45, s70, 0x3a00000
	v_and_or_b32 v0, v2, s0, v0
	s_movk_i32 s0, 0x70
	s_addc_u32 s46, s71, 0
	v_lshl_or_b32 v134, v0, 11, v1
	v_and_or_b32 v0, v2, s0, v13
	s_lshr_b32 s0, s3, 29
	s_add_i32 s0, s2, s0
	s_ashr_i32 s1, s0, 3
	s_and_b32 s0, s0, -8
	s_sub_i32 s0, s2, s0
	s_cmp_lt_i32 s0, 0
	s_movk_i32 s47, 0x161
	s_cselect_b32 s4, s47, 0x160
	s_mul_i32 s0, s0, s4
	s_add_i32 s0, s0, s1
	s_mul_hi_i32 s1, s0, 0x2e8ba2e9
	s_lshr_b32 s4, s1, 31
	s_ashr_i32 s1, s1, 5
	s_add_i32 s1, s1, s4
	s_lshl_b32 s7, s1, 3
	s_mulk_i32 s1, 0xb0
	s_sub_i32 s0, s0, s1
	s_bfe_u32 s1, s0, 0x3001c
	s_add_i32 s1, s0, s1
	s_sext_i32_i16 s4, s1
	s_and_b32 s1, s1, 0xfff8
	s_sub_i32 s0, s0, s1
	s_sext_i32_i16 s0, s0
	s_lshr_b32 s4, s4, 3
	s_add_i32 s30, s7, s0
	s_ashr_i32 s31, s30, 31
	s_bfe_i64 s[8:9], s[4:5], 0x100000
	s_lshl_b64 s[0:1], s[30:31], 19
	s_lshl_b64 s[8:9], s[8:9], 19
	s_add_u32 s38, s45, s8
	s_addc_u32 s39, s46, s9
	s_add_i32 s31, s44, 0
	s_add_i32 m0, s31, 0x10000
	v_lshl_or_b32 v130, v3, 11, v1
	global_load_lds_dwordx4 v134, s[38:39]
	s_add_i32 m0, s31, 0x12000
	s_add_u32 s8, s38, 0x40000
	global_load_lds_dwordx4 v130, s[38:39]
	s_addc_u32 s9, s39, 0
	s_add_i32 m0, s31, 0x14000
	v_lshl_or_b32 v136, v0, 11, v1
	global_load_lds_dwordx4 v134, s[8:9]
	s_add_i32 m0, s31, 0x16000
	s_add_u32 s36, s14, s0
	s_addc_u32 s37, s15, s1
	s_add_i32 s48, s31, 0x2000
	global_load_lds_dwordx4 v130, s[8:9]
	s_mov_b32 m0, s31
	s_add_u32 s0, s36, 0x40000
	global_load_lds_dwordx4 v136, s[36:37]
	s_mov_b32 m0, s48
	s_addc_u32 s1, s37, 0
	s_add_i32 s49, s31, 0x4000
	global_load_lds_dwordx4 v132, s[36:37]
	s_mov_b32 m0, s49
	s_add_i32 s50, s31, 0x6000
	global_load_lds_dwordx4 v136, s[0:1]
	s_mov_b32 m0, s50
	v_mov_b32_e32 v135, 0
	global_load_lds_dwordx4 v132, s[0:1]
	v_mov_b32_e32 v131, v135
	v_mov_b32_e32 v137, v135
	v_mov_b32_e32 v133, v135
	s_cmp_eq_u32 s10, 1
	s_mov_b32 s12, 0
	v_lshl_add_u64 v[6:7], s[38:39], 0, v[134:135]
	v_lshl_add_u64 v[4:5], s[38:39], 0, v[130:131]
	v_lshl_add_u64 v[0:1], s[36:37], 0, v[136:137]
	s_cselect_b64 s[0:1], -1, 0
	v_lshl_add_u64 v[2:3], s[36:37], 0, v[132:133]
	s_lshl_b32 s6, s6, 5
	s_and_b32 s22, s6, 0x60
	s_mov_b64 s[6:7], 0x80
	s_add_i32 m0, s31, 0x18000
	v_lshl_add_u64 v[6:7], v[6:7], 0, s[6:7]
	s_lshl_b32 s11, s10, 13
	s_lshl_b32 s23, s22, 7
	global_load_lds_dwordx4 v[6:7], off
	v_lshl_add_u64 v[4:5], v[4:5], 0, s[6:7]
	s_add_i32 m0, s31, 0x1a000
	s_add_i32 s51, s31, 0x8000
	s_add_i32 s52, s31, 0xa000
	global_load_lds_dwordx4 v[4:5], off
	v_lshl_add_u64 v[0:1], v[0:1], 0, s[6:7]
	s_mov_b32 m0, s51
	s_add_u32 s8, s38, 0x40080
	global_load_lds_dwordx4 v[0:1], off
	v_lshl_add_u64 v[0:1], v[2:3], 0, s[6:7]
	s_mov_b32 m0, s52
	s_addc_u32 s9, s39, 0
	global_load_lds_dwordx4 v[0:1], off
	s_add_i32 m0, s31, 0x1c000
	v_lshl_add_u64 v[0:1], s[8:9], 0, v[134:135]
	global_load_lds_dwordx4 v[0:1], off
	v_lshl_add_u64 v[0:1], s[8:9], 0, v[130:131]
	s_add_i32 m0, s31, 0x1e000
	s_sext_i32_i16 s13, s4
	global_load_lds_dwordx4 v[0:1], off
	v_and_b32_e32 v114, 0xff, v128
	s_lshr_b32 s98, s91, 2
	v_mov_b32_e32 v115, 0x358637bd
	s_mul_i32 s99, s98, s72
	s_add_i32 s99, s99, s2
	s_cmp_lt_u32 s99, 0xb00
	s_cselect_b32 s99, s99, s2
	s_and_b32 s100, s99, 7
	s_mul_i32 s100, s100, 0x160
	s_lshr_b32 s101, s99, 3
	s_add_i32 s100, s100, s101
	s_mul_hi_u32 s101, s100, 0x1745d18
	s_lshl_b32 s101, s101, 3
	s_and_b32 s100, s100, 7
	s_or_b32 s101, s101, s100
	s_lshl_b32 s101, s101, 8
	v_add_u32_e32 v112, s101, v114
	v_lshlrev_b32_e32 v112, 6, v112
	v_mov_b32_e32 v113, 0
	v_lshl_add_u64 v[112:113], s[18:19], 0, v[112:113]
	global_load_dwordx4 v[16:19], v[112:113], off
	global_load_dwordx4 v[20:23], v[112:113], off offset:16
	global_load_dwordx4 v[24:27], v[112:113], off offset:32
	global_load_dwordx4 v[28:31], v[112:113], off offset:48
	s_add_i32 s98, s98, 2
	s_mul_i32 s99, s98, s72
	s_add_i32 s99, s99, s2
	s_cmp_lt_u32 s99, 0xb00
	s_cselect_b32 s99, s99, s2
	s_and_b32 s100, s99, 7
	s_mul_i32 s100, s100, 0x160
	s_lshr_b32 s101, s99, 3
	s_add_i32 s100, s100, s101
	s_mul_hi_u32 s101, s100, 0x1745d18
	s_lshl_b32 s101, s101, 3
	s_and_b32 s100, s100, 7
	s_or_b32 s101, s101, s100
	s_lshl_b32 s101, s101, 8
	v_add_u32_e32 v112, s101, v114
	v_lshlrev_b32_e32 v112, 6, v112
	v_mov_b32_e32 v113, 0
	v_lshl_add_u64 v[112:113], s[18:19], 0, v[112:113]
	global_load_dwordx4 v[32:35], v[112:113], off
	global_load_dwordx4 v[36:39], v[112:113], off offset:16
	global_load_dwordx4 v[40:43], v[112:113], off offset:32
	global_load_dwordx4 v[44:47], v[112:113], off offset:48
	s_add_i32 s98, s98, 2
	s_mul_i32 s99, s98, s72
	s_add_i32 s99, s99, s2
	s_cmp_lt_u32 s99, 0xb00
	s_cselect_b32 s99, s99, s2
	s_and_b32 s100, s99, 7
	s_mul_i32 s100, s100, 0x160
	s_lshr_b32 s101, s99, 3
	s_add_i32 s100, s100, s101
	s_mul_hi_u32 s101, s100, 0x1745d18
	s_lshl_b32 s101, s101, 3
	s_and_b32 s100, s100, 7
	s_or_b32 s101, s101, s100
	s_lshl_b32 s101, s101, 8
	v_add_u32_e32 v112, s101, v114
	v_lshlrev_b32_e32 v112, 6, v112
	v_mov_b32_e32 v113, 0
	v_lshl_add_u64 v[112:113], s[18:19], 0, v[112:113]
	global_load_dwordx4 v[48:51], v[112:113], off
	global_load_dwordx4 v[52:55], v[112:113], off offset:16
	global_load_dwordx4 v[56:59], v[112:113], off offset:32
	global_load_dwordx4 v[60:63], v[112:113], off offset:48
	s_add_i32 s98, s98, 2
	s_mul_i32 s99, s98, s72
	s_add_i32 s99, s99, s2
	s_cmp_lt_u32 s99, 0xb00
	s_cselect_b32 s99, s99, s2
	s_and_b32 s100, s99, 7
	s_mul_i32 s100, s100, 0x160
	s_lshr_b32 s101, s99, 3
	s_add_i32 s100, s100, s101
	s_mul_hi_u32 s101, s100, 0x1745d18
	s_lshl_b32 s101, s101, 3
	s_and_b32 s100, s100, 7
	s_or_b32 s101, s101, s100
	s_lshl_b32 s101, s101, 8
	v_add_u32_e32 v112, s101, v114
	v_lshlrev_b32_e32 v112, 6, v112
	v_mov_b32_e32 v113, 0
	v_lshl_add_u64 v[112:113], s[18:19], 0, v[112:113]
	global_load_dwordx4 v[64:67], v[112:113], off
	global_load_dwordx4 v[68:71], v[112:113], off offset:16
	global_load_dwordx4 v[72:75], v[112:113], off offset:32
	global_load_dwordx4 v[76:79], v[112:113], off offset:48
	s_add_i32 s98, s98, 2
	s_mul_i32 s99, s98, s72
	s_add_i32 s99, s99, s2
	s_cmp_lt_u32 s99, 0xb00
	s_cselect_b32 s99, s99, s2
	s_and_b32 s100, s99, 7
	s_mul_i32 s100, s100, 0x160
	s_lshr_b32 s101, s99, 3
	s_add_i32 s100, s100, s101
	s_mul_hi_u32 s101, s100, 0x1745d18
	s_lshl_b32 s101, s101, 3
	s_and_b32 s100, s100, 7
	s_or_b32 s101, s101, s100
	s_lshl_b32 s101, s101, 8
	v_add_u32_e32 v112, s101, v114
	v_lshlrev_b32_e32 v112, 6, v112
	v_mov_b32_e32 v113, 0
	v_lshl_add_u64 v[112:113], s[18:19], 0, v[112:113]
	global_load_dwordx4 v[80:83], v[112:113], off
	global_load_dwordx4 v[84:87], v[112:113], off offset:16
	global_load_dwordx4 v[88:91], v[112:113], off offset:32
	global_load_dwordx4 v[92:95], v[112:113], off offset:48
	s_add_i32 s98, s98, 2
	s_mul_i32 s99, s98, s72
	s_add_i32 s99, s99, s2
	s_cmp_lt_u32 s99, 0xb00
	s_cselect_b32 s99, s99, s2
	s_and_b32 s100, s99, 7
	s_mul_i32 s100, s100, 0x160
	s_lshr_b32 s101, s99, 3
	s_add_i32 s100, s100, s101
	s_mul_hi_u32 s101, s100, 0x1745d18
	s_lshl_b32 s101, s101, 3
	s_and_b32 s100, s100, 7
	s_or_b32 s101, s101, s100
	s_lshl_b32 s101, s101, 8
	v_add_u32_e32 v112, s101, v114
	v_lshlrev_b32_e32 v112, 6, v112
	v_mov_b32_e32 v113, 0
	v_lshl_add_u64 v[112:113], s[18:19], 0, v[112:113]
	global_load_dwordx4 v[96:99], v[112:113], off
	global_load_dwordx4 v[100:103], v[112:113], off offset:16
	global_load_dwordx4 v[104:107], v[112:113], off offset:32
	global_load_dwordx4 v[108:111], v[112:113], off offset:48
	s_add_i32 s98, s98, 2
	v_lshlrev_b32_e32 v116, 2, v128
	v_add_u32_e32 v116, 0x20000, v116
	s_waitcnt vmcnt(20)
	v_pk_add_f32 v[118:119], v[18:19], v[22:23]
	v_pk_add_f32 v[120:121], v[16:17], v[20:21]
	v_pk_add_f32 v[122:123], v[26:27], v[30:31]
	v_pk_add_f32 v[124:125], v[24:25], v[28:29]
	v_pk_add_f32 v[118:119], v[118:119], v[122:123]
	v_pk_add_f32 v[120:121], v[120:121], v[124:125]
	v_add_f32_e32 v120, v121, v120
	v_add_f32_e32 v118, v118, v119
	v_add_f32_e32 v118, v120, v118
	v_fmamk_f32 v118, v118, 0x3a800000, v115
	v_rsq_f32_e32 v118, v118
	ds_write_b32 v116, v118
	s_waitcnt vmcnt(16)
	v_pk_add_f32 v[118:119], v[34:35], v[38:39]
	v_pk_add_f32 v[120:121], v[32:33], v[36:37]
	v_pk_add_f32 v[122:123], v[42:43], v[46:47]
	v_pk_add_f32 v[124:125], v[40:41], v[44:45]
	v_pk_add_f32 v[118:119], v[118:119], v[122:123]
	v_pk_add_f32 v[120:121], v[120:121], v[124:125]
	v_add_f32_e32 v120, v121, v120
	v_add_f32_e32 v118, v118, v119
	v_add_f32_e32 v118, v120, v118
	v_fmamk_f32 v118, v118, 0x3a800000, v115
	v_rsq_f32_e32 v118, v118
	ds_write_b32 v116, v118 offset:2048
	s_waitcnt vmcnt(12)
	v_pk_add_f32 v[118:119], v[50:51], v[54:55]
	v_pk_add_f32 v[120:121], v[48:49], v[52:53]
	v_pk_add_f32 v[122:123], v[58:59], v[62:63]
	v_pk_add_f32 v[124:125], v[56:57], v[60:61]
	v_pk_add_f32 v[118:119], v[118:119], v[122:123]
	v_pk_add_f32 v[120:121], v[120:121], v[124:125]
	v_add_f32_e32 v120, v121, v120
	v_add_f32_e32 v118, v118, v119
	v_add_f32_e32 v118, v120, v118
	v_fmamk_f32 v118, v118, 0x3a800000, v115
	v_rsq_f32_e32 v118, v118
	ds_write_b32 v116, v118 offset:4096
	s_waitcnt vmcnt(8)
	v_pk_add_f32 v[118:119], v[66:67], v[70:71]
	v_pk_add_f32 v[120:121], v[64:65], v[68:69]
	v_pk_add_f32 v[122:123], v[74:75], v[78:79]
	v_pk_add_f32 v[124:125], v[72:73], v[76:77]
	v_pk_add_f32 v[118:119], v[118:119], v[122:123]
	v_pk_add_f32 v[120:121], v[120:121], v[124:125]
	v_add_f32_e32 v120, v121, v120
	v_add_f32_e32 v118, v118, v119
	v_add_f32_e32 v118, v120, v118
	v_fmamk_f32 v118, v118, 0x3a800000, v115
	v_rsq_f32_e32 v118, v118
	ds_write_b32 v116, v118 offset:6144
	s_waitcnt vmcnt(4)
	v_pk_add_f32 v[118:119], v[82:83], v[86:87]
	v_pk_add_f32 v[120:121], v[80:81], v[84:85]
	v_pk_add_f32 v[122:123], v[90:91], v[94:95]
	v_pk_add_f32 v[124:125], v[88:89], v[92:93]
	v_pk_add_f32 v[118:119], v[118:119], v[122:123]
	v_pk_add_f32 v[120:121], v[120:121], v[124:125]
	v_add_f32_e32 v120, v121, v120
	v_add_f32_e32 v118, v118, v119
	v_add_f32_e32 v118, v120, v118
	v_fmamk_f32 v118, v118, 0x3a800000, v115
	v_rsq_f32_e32 v118, v118
	ds_write_b32 v116, v118 offset:8192
	s_waitcnt vmcnt(0)
	v_pk_add_f32 v[118:119], v[98:99], v[102:103]
	v_pk_add_f32 v[120:121], v[96:97], v[100:101]
	v_pk_add_f32 v[122:123], v[106:107], v[110:111]
	v_pk_add_f32 v[124:125], v[104:105], v[108:109]
	v_pk_add_f32 v[118:119], v[118:119], v[122:123]
	v_pk_add_f32 v[120:121], v[120:121], v[124:125]
	v_add_f32_e32 v120, v121, v120
	v_add_f32_e32 v118, v118, v119
	v_add_f32_e32 v118, v120, v118
	v_fmamk_f32 v118, v118, 0x3a800000, v115
	v_rsq_f32_e32 v118, v118
	ds_write_b32 v116, v118 offset:10240
	s_cmp_lg_u32 s10, 1
	s_cbranch_scc1 .LBB0_1641
	s_barrier
.LBB0_1641:
	s_waitcnt vmcnt(8) lgkmcnt(0)
	s_barrier
	v_and_b32_e32 v0, 15, v128
	v_lshlrev_b32_e32 v1, 1, v12
	v_lshl_or_b32 v150, s10, 6, v0
	v_lshl_or_b32 v2, v0, 6, v1
	v_lshlrev_b32_e32 v0, 2, v0
	v_and_b32_e32 v3, 32, v0
	v_bitop3_b32 v2, v2, s11, v3 bitop3:0xde
	v_lshlrev_b32_e32 v3, 6, v128
	s_movk_i32 s4, 0x3c0
	s_cmpk_lt_u32 s5, 0x100
	v_and_or_b32 v1, v3, s4, v1
	s_cselect_b64 s[8:9], -1, 0
	s_lshl_b32 s4, s10, 8
	s_add_i32 s4, s4, 0
	s_add_i32 s4, s4, 0x20000
	v_and_b32_e32 v3, 32, v8
	v_add_u32_e32 v152, s4, v0
	v_lshlrev_b32_e32 v0, 8, v128
	v_bitop3_b32 v151, s23, v1, v3 bitop3:0xf6
	v_and_b32_e32 v0, 0x38000, v0
	v_lshlrev_b32_e32 v1, 11, v13
	v_or3_b32 v0, v10, v0, v1
	v_add_u32_e32 v138, v0, v11
	v_lshlrev_b32_e32 v0, 4, v9
	s_waitcnt vmcnt(6)
	v_and_b32_e32 v0, 0x78000, v0
	v_or3_b32 v0, v10, v0, v1
	s_add_i32 s53, 0, 0x10000
	s_add_i32 s54, 0, 0x14000
	v_or_b32_e32 v153, s22, v12
	v_mov_b32_e32 v139, v135
	v_add_u32_e32 v140, v0, v11
	v_mov_b32_e32 v141, v135
	v_mov_b64_e32 v[142:143], 0xb00
	v_mov_b64_e32 v[144:145], 0xaff
	v_add_u32_e32 v154, s53, v151
	v_add_u32_e32 v155, s54, v151
	v_add_u32_e32 v157, 0, v2
	s_movk_i32 s55, 0x1600
	s_mov_b32 s56, 0
	s_barrier
	s_branch .LBB0_1644

.LBB0_1818:
	v_lshrrev_b32_e32 v2, 1, v128
	v_and_b32_e32 v130, 24, v2
	v_lshrrev_b32_e32 v2, 5, v128
	v_and_b32_e32 v2, 4, v2
	v_bfe_u32 v3, v128, 2, 2
	v_lshlrev_b32_e32 v0, 4, v128
	v_and_b32_e32 v1, 32, v128
	v_bfe_u32 v11, v128, 2, 4
	v_or3_b32 v2, v2, v3, v130
	v_lshrrev_b32_e32 v3, 3, v128
	s_movk_i32 s1, 0x70
	v_bitop3_b32 v9, v0, v1, 48 bitop3:0x6c
	v_and_b32_e32 v10, 64, v128
	v_and_or_b32 v4, v3, s1, v11
	s_movk_i32 s1, 0x60
	v_add_u32_e32 v12, 0x2000, v0
	s_lshr_b32 s5, s8, 6
	s_lshr_b32 s4, s8, 8
	v_or_b32_e32 v1, v9, v10
	v_and_or_b32 v3, v3, s1, v2
	v_lshrrev_b32_e32 v0, 7, v12
	s_movk_i32 s1, 0xf0
	s_lshl_b32 s50, s5, 10
	v_lshl_or_b32 v134, v3, 11, v1
	v_and_or_b32 v3, v0, s1, v11
	s_movk_i32 s1, 0xe0
	s_add_u32 s51, s70, 0x4a80000
	v_and_or_b32 v0, v0, s1, v2
	s_addc_u32 s52, s71, 0
	s_ashr_i32 s7, s6, 31
	s_ashr_i32 s1, s0, 31
	s_lshl_b64 s[10:11], s[6:7], 19
	s_lshl_b64 s[12:13], s[0:1], 19
	s_add_u32 s44, s51, s12
	s_addc_u32 s45, s52, s13
	s_add_i32 s53, s50, 0
	s_add_i32 m0, s53, 0x10000
	v_lshl_or_b32 v138, v0, 11, v1
	global_load_lds_dwordx4 v134, s[44:45]
	s_add_i32 m0, s53, 0x12000
	s_add_u32 s12, s44, 0x40000
	global_load_lds_dwordx4 v138, s[44:45]
	s_addc_u32 s13, s45, 0
	s_add_i32 m0, s53, 0x14000
	v_lshl_or_b32 v132, v4, 11, v1
	global_load_lds_dwordx4 v134, s[12:13]
	s_add_i32 m0, s53, 0x16000
	s_add_u32 s42, s14, s10
	s_addc_u32 s43, s15, s11
	s_add_i32 s54, s53, 0x2000
	global_load_lds_dwordx4 v138, s[12:13]
	s_mov_b32 m0, s53
	s_add_u32 s10, s42, 0x40000
	v_lshl_or_b32 v136, v3, 11, v1
	global_load_lds_dwordx4 v132, s[42:43]
	s_mov_b32 m0, s54
	s_addc_u32 s11, s43, 0
	s_add_i32 s55, s53, 0x4000
	global_load_lds_dwordx4 v136, s[42:43]
	s_mov_b32 m0, s55
	s_add_i32 s56, s53, 0x6000
	global_load_lds_dwordx4 v132, s[10:11]
	s_mov_b32 m0, s56
	v_mov_b32_e32 v141, 0
	global_load_lds_dwordx4 v136, s[10:11]
	v_mov_b32_e32 v135, v141
	v_mov_b32_e32 v139, v141
	v_mov_b32_e32 v133, v141
	v_mov_b32_e32 v137, v141
	s_cmp_eq_u32 s4, 1
	s_mov_b32 s9, 0
	v_lshl_add_u64 v[6:7], s[44:45], 0, v[134:135]
	v_lshl_add_u64 v[4:5], s[44:45], 0, v[138:139]
	v_lshl_add_u64 v[0:1], s[42:43], 0, v[132:133]
	s_cselect_b64 s[10:11], -1, 0
	v_lshl_add_u64 v[2:3], s[42:43], 0, v[136:137]
	s_add_u32 s22, s70, 0x13700000
	s_addc_u32 s23, s71, 0
	s_lshl_b32 s5, s5, 5
	s_mov_b64 s[26:27], 0x80
	s_and_b32 s57, s5, 0x60
	s_add_i32 m0, s53, 0x18000
	v_lshl_add_u64 v[6:7], v[6:7], 0, s[26:27]
	s_lshl_b32 s1, s4, 13
	s_lshl_b32 s5, s57, 7
	global_load_lds_dwordx4 v[6:7], off
	v_lshl_add_u64 v[4:5], v[4:5], 0, s[26:27]
	s_add_i32 m0, s53, 0x1a000
	s_add_i32 s58, s53, 0x8000
	s_add_i32 s59, s53, 0xa000
	global_load_lds_dwordx4 v[4:5], off
	v_lshl_add_u64 v[0:1], v[0:1], 0, s[26:27]
	s_mov_b32 m0, s58
	s_add_u32 s12, s44, 0x40080
	global_load_lds_dwordx4 v[0:1], off
	v_lshl_add_u64 v[0:1], v[2:3], 0, s[26:27]
	s_mov_b32 m0, s59
	s_addc_u32 s13, s45, 0
	global_load_lds_dwordx4 v[0:1], off
	s_add_i32 m0, s53, 0x1c000
	v_lshl_add_u64 v[0:1], s[12:13], 0, v[134:135]
	global_load_lds_dwordx4 v[0:1], off
	v_lshl_add_u64 v[0:1], s[12:13], 0, v[138:139]
	s_add_i32 m0, s53, 0x1e000
	global_load_lds_dwordx4 v[0:1], off
	v_and_b32_e32 v114, 0xff, v128
	s_lshr_b32 s98, s91, 2
	v_mov_b32_e32 v115, 0x358637bd
	s_mul_i32 s99, s98, s72
	s_add_i32 s99, s99, s2
	s_cmp_lt_u32 s99, 0x600
	s_cselect_b32 s99, s99, s2
	s_and_b32 s100, s99, 7
	s_mul_i32 s100, s100, 0xc0
	s_lshr_b32 s101, s99, 3
	s_add_i32 s100, s100, s101
	s_mul_hi_u32 s101, s100, 0x2aaaaab
	s_lshl_b32 s101, s101, 3
	s_and_b32 s100, s100, 7
	s_or_b32 s101, s101, s100
	s_lshl_b32 s101, s101, 8
	v_add_u32_e32 v112, s101, v114
	v_lshlrev_b32_e32 v112, 6, v112
	v_mov_b32_e32 v113, 0
	v_lshl_add_u64 v[112:113], s[18:19], 0, v[112:113]
	global_load_dwordx4 v[16:19], v[112:113], off
	global_load_dwordx4 v[20:23], v[112:113], off offset:16
	global_load_dwordx4 v[24:27], v[112:113], off offset:32
	global_load_dwordx4 v[28:31], v[112:113], off offset:48
	s_add_i32 s98, s98, 2
	s_mul_i32 s99, s98, s72
	s_add_i32 s99, s99, s2
	s_cmp_lt_u32 s99, 0x600
	s_cselect_b32 s99, s99, s2
	s_and_b32 s100, s99, 7
	s_mul_i32 s100, s100, 0xc0
	s_lshr_b32 s101, s99, 3
	s_add_i32 s100, s100, s101
	s_mul_hi_u32 s101, s100, 0x2aaaaab
	s_lshl_b32 s101, s101, 3
	s_and_b32 s100, s100, 7
	s_or_b32 s101, s101, s100
	s_lshl_b32 s101, s101, 8
	v_add_u32_e32 v112, s101, v114
	v_lshlrev_b32_e32 v112, 6, v112
	v_mov_b32_e32 v113, 0
	v_lshl_add_u64 v[112:113], s[18:19], 0, v[112:113]
	global_load_dwordx4 v[32:35], v[112:113], off
	global_load_dwordx4 v[36:39], v[112:113], off offset:16
	global_load_dwordx4 v[40:43], v[112:113], off offset:32
	global_load_dwordx4 v[44:47], v[112:113], off offset:48
	s_add_i32 s98, s98, 2
	s_mul_i32 s99, s98, s72
	s_add_i32 s99, s99, s2
	s_cmp_lt_u32 s99, 0x600
	s_cselect_b32 s99, s99, s2
	s_and_b32 s100, s99, 7
	s_mul_i32 s100, s100, 0xc0
	s_lshr_b32 s101, s99, 3
	s_add_i32 s100, s100, s101
	s_mul_hi_u32 s101, s100, 0x2aaaaab
	s_lshl_b32 s101, s101, 3
	s_and_b32 s100, s100, 7
	s_or_b32 s101, s101, s100
	s_lshl_b32 s101, s101, 8
	v_add_u32_e32 v112, s101, v114
	v_lshlrev_b32_e32 v112, 6, v112
	v_mov_b32_e32 v113, 0
	v_lshl_add_u64 v[112:113], s[18:19], 0, v[112:113]
	global_load_dwordx4 v[48:51], v[112:113], off
	global_load_dwordx4 v[52:55], v[112:113], off offset:16
	global_load_dwordx4 v[56:59], v[112:113], off offset:32
	global_load_dwordx4 v[60:63], v[112:113], off offset:48
	s_add_i32 s98, s98, 2
	v_lshlrev_b32_e32 v116, 2, v128
	v_add_u32_e32 v116, 0x20000, v116
	s_waitcnt vmcnt(8)
	v_pk_add_f32 v[118:119], v[18:19], v[22:23]
	v_pk_add_f32 v[120:121], v[16:17], v[20:21]
	v_pk_add_f32 v[122:123], v[26:27], v[30:31]
	v_pk_add_f32 v[124:125], v[24:25], v[28:29]
	v_pk_add_f32 v[118:119], v[118:119], v[122:123]
	v_pk_add_f32 v[120:121], v[120:121], v[124:125]
	v_add_f32_e32 v120, v121, v120
	v_add_f32_e32 v118, v118, v119
	v_add_f32_e32 v118, v120, v118
	v_fmamk_f32 v118, v118, 0x3a800000, v115
	v_rsq_f32_e32 v118, v118
	ds_write_b32 v116, v118
	s_waitcnt vmcnt(4)
	v_pk_add_f32 v[118:119], v[34:35], v[38:39]
	v_pk_add_f32 v[120:121], v[32:33], v[36:37]
	v_pk_add_f32 v[122:123], v[42:43], v[46:47]
	v_pk_add_f32 v[124:125], v[40:41], v[44:45]
	v_pk_add_f32 v[118:119], v[118:119], v[122:123]
	v_pk_add_f32 v[120:121], v[120:121], v[124:125]
	v_add_f32_e32 v120, v121, v120
	v_add_f32_e32 v118, v118, v119
	v_add_f32_e32 v118, v120, v118
	v_fmamk_f32 v118, v118, 0x3a800000, v115
	v_rsq_f32_e32 v118, v118
	ds_write_b32 v116, v118 offset:2048
	s_waitcnt vmcnt(0)
	v_pk_add_f32 v[118:119], v[50:51], v[54:55]
	v_pk_add_f32 v[120:121], v[48:49], v[52:53]
	v_pk_add_f32 v[122:123], v[58:59], v[62:63]
	v_pk_add_f32 v[124:125], v[56:57], v[60:61]
	v_pk_add_f32 v[118:119], v[118:119], v[122:123]
	v_pk_add_f32 v[120:121], v[120:121], v[124:125]
	v_add_f32_e32 v120, v121, v120
	v_add_f32_e32 v118, v118, v119
	v_add_f32_e32 v118, v120, v118
	v_fmamk_f32 v118, v118, 0x3a800000, v115
	v_rsq_f32_e32 v118, v118
	ds_write_b32 v116, v118 offset:4096
	s_cmp_lg_u32 s4, 1
	s_cbranch_scc1 .LBB0_1820
	s_barrier
.LBB0_1820:
	s_waitcnt vmcnt(8) lgkmcnt(0)
	s_barrier
	s_cmpk_lt_u32 s8, 0x100
	v_and_b32_e32 v0, 15, v128
	v_lshlrev_b32_e32 v1, 1, v130
	v_lshl_or_b32 v131, s4, 6, v0
	v_lshl_or_b32 v2, v0, 6, v1
	v_lshlrev_b32_e32 v0, 2, v0
	v_and_b32_e32 v3, 32, v0
	v_bitop3_b32 v2, v2, s1, v3 bitop3:0xde
	v_lshlrev_b32_e32 v3, 6, v128
	s_movk_i32 s1, 0x3c0
	v_and_or_b32 v1, v3, s1, v1
	s_cselect_b64 s[28:29], -1, 0
	s_lshl_b32 s1, s4, 8
	s_add_i32 s1, s1, 0
	s_add_i32 s1, s1, 0x20000
	v_and_b32_e32 v3, 32, v8
	v_add_u32_e32 v155, s1, v0
	v_lshlrev_b32_e32 v0, 8, v128
	v_bitop3_b32 v154, s5, v1, v3 bitop3:0xf6
	v_and_b32_e32 v0, 0x38000, v0
	v_lshlrev_b32_e32 v1, 11, v11
	v_or3_b32 v0, v9, v0, v1
	v_add_u32_e32 v142, v0, v10
	v_lshlrev_b32_e32 v0, 4, v12
	s_waitcnt vmcnt(6)
	v_and_b32_e32 v0, 0x78000, v0
	v_or3_b32 v0, v9, v0, v1
	s_add_i32 s61, 0, 0x10000
	s_add_i32 s62, 0, 0x14000
	v_mov_b32_e32 v143, v141
	v_add_u32_e32 v144, v0, v10
	v_mov_b32_e32 v145, v141
	v_mov_b64_e32 v[146:147], 0x600
	v_mov_b64_e32 v[148:149], 0x5ff
	s_movk_i32 s60, 0xc1
	v_add_u32_e32 v157, s61, v154
	v_add_u32_e32 v158, s62, v154
	v_add_u32_e32 v159, 0, v2
	s_mov_b32 s1, 0
	s_mov_b32 s63, 0
	s_barrier
	s_branch .LBB0_1823
